# merge GEMM epilogues (gate*acc, +=): gate/MIX loads hoisted and batched into dead fragment registers (1-3 waits instead of 16-32 load-wait-store round trips); attention softmax+PV hand-scheduled with
# speedup vs baseline: 1.0157x; 1.0157x over previous
; template <bool MLA>
; DI void attn_unit(LAS unsigned char* lds, const bf16* Qp, int qstride, const bf16* Kp, int kstride, const bf16* KRp, const bf16* Vp, int vstride,
;                   bf16* Op, int ostride, int t_lo, int t_hi, int qc, bool active, int wave, int lane) {
;     ...
;             float mx = s0[0];
; #pragma unroll
;             for (int i = 1; i < 16; ++i) mx = fmaxf(mx, s0[i]);
; #pragma unroll
;             for (int i = 0; i < 16; ++i) mx = fmaxf(mx, s1[i]);
;             mx = fmaxf(mx, __shfl_xor(mx, 32));
;             const float m_new = fmaxf(m_run, mx);
;             const float alpha = __builtin_amdgcn_exp2f(m_run - m_new);
;             m_run = m_new;
;             float ps = 0.f;
; #pragma unroll
;             for (int i = 0; i < 16; ++i) { s0[i] = __builtin_amdgcn_exp2f(s0[i] - m_new); s1[i] = __builtin_amdgcn_exp2f(s1[i] - m_new); ps += s0[i] + s1[i]; }
;             l_run = l_run * alpha + ps;
; #pragma unroll
;             for (int d = 0; d < 4; ++d)
; #pragma unroll
;                 for (int i = 0; i < 16; ++i) o[d][i] *= alpha;
.LBB0_598:
	v_add_u32_e32 v198, s85, v186
	ds_read_b64_tr_b16 v[64:65], v198 offset:16384
	ds_read_b64_tr_b16 v[66:67], v198 offset:18432
	ds_read_b64_tr_b16 v[68:69], v198 offset:16896
	ds_read_b64_tr_b16 v[70:71], v198 offset:18944
	ds_read_b64_tr_b16 v[72:73], v198 offset:17408
	ds_read_b64_tr_b16 v[74:75], v198 offset:19456
	ds_read_b64_tr_b16 v[76:77], v198 offset:17920
	ds_read_b64_tr_b16 v[78:79], v198 offset:19968
	v_max3_f32 v91, v150, v151, v148
	v_max3_f32 v92, v149, v174, v175
	v_max3_f32 v91, v91, v170, v171
	v_max3_f32 v92, v92, v166, v167
	v_max3_f32 v91, v91, v162, v163
	v_max3_f32 v92, v92, v158, v159
	v_max3_f32 v91, v91, v156, v157
	v_max3_f32 v92, v92, v154, v155
	v_max3_f32 v91, v91, v152, v153
	v_max3_f32 v92, v92, v180, v181
	v_max3_f32 v91, v91, v178, v179
	v_max3_f32 v92, v92, v176, v177
	v_max3_f32 v91, v91, v172, v173
	v_max3_f32 v92, v92, v168, v169
	v_max3_f32 v91, v91, v164, v165
	v_max_f32_e32 v91, v91, v92
	v_mov_b32_e32 v92, v91
	s_nop 1
	v_permlane32_swap_b32_e32 v91, v92
	s_nop 0
	v_max3_f32 v90, v192, v91, v92
	v_sub_f32_e32 v88, v192, v90
	v_cmp_gt_f32_e32 vcc, 0xc1000000, v88
	s_cbranch_vccnz .Lresc_band
	v_mov_b32_e32 v90, v192
	v_mov_b32_e32 v88, 1.0
	s_branch .Lresc_done_band
.Lresc_band:
	v_exp_f32_e32 v88, v88
	s_nop 0
	v_pk_mul_f32 v[48:49], v[48:49], v[88:89] op_sel_hi:[1,0]
	v_pk_mul_f32 v[50:51], v[50:51], v[88:89] op_sel_hi:[1,0]
	v_pk_mul_f32 v[52:53], v[52:53], v[88:89] op_sel_hi:[1,0]
	v_pk_mul_f32 v[54:55], v[54:55], v[88:89] op_sel_hi:[1,0]
	v_pk_mul_f32 v[56:57], v[56:57], v[88:89] op_sel_hi:[1,0]
	v_pk_mul_f32 v[58:59], v[58:59], v[88:89] op_sel_hi:[1,0]
	v_pk_mul_f32 v[60:61], v[60:61], v[88:89] op_sel_hi:[1,0]
	v_pk_mul_f32 v[62:63], v[62:63], v[88:89] op_sel_hi:[1,0]
	v_pk_mul_f32 v[32:33], v[32:33], v[88:89] op_sel_hi:[1,0]
	v_pk_mul_f32 v[34:35], v[34:35], v[88:89] op_sel_hi:[1,0]
	v_pk_mul_f32 v[36:37], v[36:37], v[88:89] op_sel_hi:[1,0]
	v_pk_mul_f32 v[38:39], v[38:39], v[88:89] op_sel_hi:[1,0]
	v_pk_mul_f32 v[40:41], v[40:41], v[88:89] op_sel_hi:[1,0]
	v_pk_mul_f32 v[42:43], v[42:43], v[88:89] op_sel_hi:[1,0]
	v_pk_mul_f32 v[44:45], v[44:45], v[88:89] op_sel_hi:[1,0]
	v_pk_mul_f32 v[46:47], v[46:47], v[88:89] op_sel_hi:[1,0]
	v_pk_mul_f32 v[16:17], v[16:17], v[88:89] op_sel_hi:[1,0]
	v_pk_mul_f32 v[18:19], v[18:19], v[88:89] op_sel_hi:[1,0]
	v_pk_mul_f32 v[20:21], v[20:21], v[88:89] op_sel_hi:[1,0]
	v_pk_mul_f32 v[22:23], v[22:23], v[88:89] op_sel_hi:[1,0]
	v_pk_mul_f32 v[24:25], v[24:25], v[88:89] op_sel_hi:[1,0]
	v_pk_mul_f32 v[26:27], v[26:27], v[88:89] op_sel_hi:[1,0]
	v_pk_mul_f32 v[28:29], v[28:29], v[88:89] op_sel_hi:[1,0]
	v_pk_mul_f32 v[30:31], v[30:31], v[88:89] op_sel_hi:[1,0]
	v_pk_mul_f32 v[0:1], v[0:1], v[88:89] op_sel_hi:[1,0]
	v_pk_mul_f32 v[2:3], v[2:3], v[88:89] op_sel_hi:[1,0]
	v_pk_mul_f32 v[4:5], v[4:5], v[88:89] op_sel_hi:[1,0]
	v_pk_mul_f32 v[6:7], v[6:7], v[88:89] op_sel_hi:[1,0]
	v_pk_mul_f32 v[8:9], v[8:9], v[88:89] op_sel_hi:[1,0]
	v_pk_mul_f32 v[10:11], v[10:11], v[88:89] op_sel_hi:[1,0]
	v_pk_mul_f32 v[12:13], v[12:13], v[88:89] op_sel_hi:[1,0]
	v_pk_mul_f32 v[14:15], v[14:15], v[88:89] op_sel_hi:[1,0]
; DI unsigned pk2(float lo, float hi) { f32x2_t v = {lo, hi}; bf16x2_t b = __builtin_convertvector(v, bf16x2_t); return __builtin_bit_cast(unsigned, b); }
; #define MFMA32(a, b, c) __builtin_amdgcn_mfma_f32_32x32x16_bf16((a), (b), (c), 0, 0, 0)
; DI s16x4 vtr(const LAS unsigned char* p) { return __builtin_bit_cast(s16x4, __builtin_amdgcn_ds_read_tr16_b64_v4i16((LAS v4i16_t*)p)); }
; template <bool MLA>
; DI void attn_unit(LAS unsigned char* lds, const bf16* Qp, int qstride, const bf16* Kp, int kstride, const bf16* KRp, const bf16* Vp, int vstride,
;                   bf16* Op, int ostride, int t_lo, int t_hi, int qc, bool active, int wave, int lane) {
;     ...
;             float ps = 0.f;
; #pragma unroll
;             for (int i = 0; i < 16; ++i) { s0[i] = __builtin_amdgcn_exp2f(s0[i] - m_new); s1[i] = __builtin_amdgcn_exp2f(s1[i] - m_new); ps += s0[i] + s1[i]; }
;             l_run = l_run * alpha + ps;
; #pragma unroll
;             for (int d = 0; d < 4; ++d)
; #pragma unroll
;                 for (int i = 0; i < 16; ++i) o[d][i] *= alpha;
; #pragma unroll
;             for (int kt = 0; kt < 2; ++kt) {
; #pragma unroll
;                 for (int s = 0; s < 2; ++s) {
;                     u32x4 pw;
;                     if (kt == 0) { pw.x = pk2(s0[8 * s], s0[8 * s + 1]); pw.y = pk2(s0[8 * s + 2], s0[8 * s + 3]); pw.z = pk2(s0[8 * s + 4], s0[8 * s + 5]); pw.w = pk2(s0[8 * s + 6], s0[8 * s + 7]); }
;                     else { pw.x = pk2(s1[8 * s], s1[8 * s + 1]); pw.y = pk2(s1[8 * s + 2], s1[8 * s + 3]); pw.z = pk2(s1[8 * s + 4], s1[8 * s + 5]); pw.w = pk2(s1[8 * s + 6], s1[8 * s + 7]); }
;                     const bf16x8 pb = __builtin_bit_cast(bf16x8, pw);
; #pragma unroll
;                     for (int dt = 0; dt < 4; ++dt) {
;                         const s16x4 lo = vtr(buf + AT_V + ((4 * kt + 2 * s) * 4 + dt) * 512 + voff);
;                         const s16x4 hi = vtr(buf + AT_V + ((4 * kt + 2 * s + 1) * 4 + dt) * 512 + voff);
;                         const bf16x8 va = __builtin_shufflevector(lo, hi, 0, 1, 2, 3, 4, 5, 6, 7);
;                         o[dt] = MFMA32(va, pb, o[dt]);
;                     }
;                     __builtin_amdgcn_sched_barrier(0);
;                 }
;             }
.Lresc_done_band:
	v_sub_f32_e32 v150, v150, v90
	v_sub_f32_e32 v151, v151, v90
	v_sub_f32_e32 v148, v148, v90
	v_sub_f32_e32 v149, v149, v90
	v_sub_f32_e32 v174, v174, v90
	v_sub_f32_e32 v175, v175, v90
	v_sub_f32_e32 v170, v170, v90
	v_sub_f32_e32 v171, v171, v90
	v_exp_f32_e32 v150, v150
	v_exp_f32_e32 v151, v151
	v_exp_f32_e32 v148, v148
	v_exp_f32_e32 v149, v149
	v_exp_f32_e32 v174, v174
	v_exp_f32_e32 v175, v175
	v_exp_f32_e32 v170, v170
	v_exp_f32_e32 v171, v171
	v_add_f32_e32 v93, v150, v151
	v_add_f32_e32 v94, v148, v149
	v_add_f32_e32 v93, v93, v174
	v_add_f32_e32 v94, v94, v175
	v_add_f32_e32 v93, v93, v170
	v_add_f32_e32 v94, v94, v171
	v_cvt_pk_bf16_f32 v80, v150, v151
	v_cvt_pk_bf16_f32 v81, v148, v149
	v_cvt_pk_bf16_f32 v82, v174, v175
	v_cvt_pk_bf16_f32 v83, v170, v171
	s_nop 0
	v_sub_f32_e32 v166, v166, v90
	v_sub_f32_e32 v167, v167, v90
	v_sub_f32_e32 v162, v162, v90
	v_sub_f32_e32 v163, v163, v90
	v_sub_f32_e32 v158, v158, v90
	v_sub_f32_e32 v159, v159, v90
	v_sub_f32_e32 v156, v156, v90
	v_sub_f32_e32 v157, v157, v90
	s_waitcnt lgkmcnt(6)
	v_mfma_f32_32x32x16_bf16 v[48:63], v[64:67], v[80:83], v[48:63]
	ds_read_b64_tr_b16 v[64:65], v198 offset:20480
	ds_read_b64_tr_b16 v[66:67], v198 offset:22528
	v_exp_f32_e32 v166, v166
	v_exp_f32_e32 v167, v167
	s_waitcnt lgkmcnt(6)
	v_mfma_f32_32x32x16_bf16 v[32:47], v[68:71], v[80:83], v[32:47]
	ds_read_b64_tr_b16 v[68:69], v198 offset:20992
	ds_read_b64_tr_b16 v[70:71], v198 offset:23040
	v_exp_f32_e32 v162, v162
	v_exp_f32_e32 v163, v163
	s_waitcnt lgkmcnt(6)
	v_mfma_f32_32x32x16_bf16 v[16:31], v[72:75], v[80:83], v[16:31]
	ds_read_b64_tr_b16 v[72:73], v198 offset:21504
	ds_read_b64_tr_b16 v[74:75], v198 offset:23552
	v_exp_f32_e32 v158, v158
	v_exp_f32_e32 v159, v159
	s_waitcnt lgkmcnt(6)
	v_mfma_f32_32x32x16_bf16 v[0:15], v[76:79], v[80:83], v[0:15]
	ds_read_b64_tr_b16 v[76:77], v198 offset:22016
	ds_read_b64_tr_b16 v[78:79], v198 offset:24064
	v_exp_f32_e32 v156, v156
	v_exp_f32_e32 v157, v157
	v_sub_f32_e32 v154, v154, v90
	v_sub_f32_e32 v155, v155, v90
	v_sub_f32_e32 v152, v152, v90
	v_sub_f32_e32 v153, v153, v90
	v_sub_f32_e32 v180, v180, v90
	v_sub_f32_e32 v181, v181, v90
	v_sub_f32_e32 v178, v178, v90
	v_sub_f32_e32 v179, v179, v90
	v_add_f32_e32 v93, v93, v166
	v_add_f32_e32 v94, v94, v167
	v_add_f32_e32 v93, v93, v162
	v_add_f32_e32 v94, v94, v163
	v_add_f32_e32 v93, v93, v158
	v_add_f32_e32 v94, v94, v159
	v_add_f32_e32 v93, v93, v156
	v_add_f32_e32 v94, v94, v157
	v_cvt_pk_bf16_f32 v84, v166, v167
	v_cvt_pk_bf16_f32 v85, v162, v163
	v_cvt_pk_bf16_f32 v86, v158, v159
	v_cvt_pk_bf16_f32 v87, v156, v157
	v_exp_f32_e32 v154, v154
	s_waitcnt lgkmcnt(6)
	v_mfma_f32_32x32x16_bf16 v[48:63], v[64:67], v[84:87], v[48:63]
	ds_read_b64_tr_b16 v[64:65], v198 offset:24576
	ds_read_b64_tr_b16 v[66:67], v198 offset:26624
	v_exp_f32_e32 v155, v155
	v_exp_f32_e32 v152, v152
	s_waitcnt lgkmcnt(6)
	v_mfma_f32_32x32x16_bf16 v[32:47], v[68:71], v[84:87], v[32:47]
	ds_read_b64_tr_b16 v[68:69], v198 offset:25088
	ds_read_b64_tr_b16 v[70:71], v198 offset:27136
	v_exp_f32_e32 v153, v153
	v_exp_f32_e32 v180, v180
	s_waitcnt lgkmcnt(6)
	v_mfma_f32_32x32x16_bf16 v[16:31], v[72:75], v[84:87], v[16:31]
	ds_read_b64_tr_b16 v[72:73], v198 offset:25600
	ds_read_b64_tr_b16 v[74:75], v198 offset:27648
	v_exp_f32_e32 v181, v181
	v_exp_f32_e32 v178, v178
	s_waitcnt lgkmcnt(6)
	v_mfma_f32_32x32x16_bf16 v[0:15], v[76:79], v[84:87], v[0:15]
	ds_read_b64_tr_b16 v[76:77], v198 offset:26112
	ds_read_b64_tr_b16 v[78:79], v198 offset:28160
	v_exp_f32_e32 v179, v179
	v_sub_f32_e32 v176, v176, v90
	v_sub_f32_e32 v177, v177, v90
	v_sub_f32_e32 v172, v172, v90
	v_sub_f32_e32 v173, v173, v90
	v_sub_f32_e32 v168, v168, v90
	v_sub_f32_e32 v169, v169, v90
	v_sub_f32_e32 v164, v164, v90
	v_sub_f32_e32 v165, v165, v90
	v_add_f32_e32 v93, v93, v154
	v_add_f32_e32 v94, v94, v155
	v_add_f32_e32 v93, v93, v152
	v_add_f32_e32 v94, v94, v153
	v_add_f32_e32 v93, v93, v180
	v_add_f32_e32 v94, v94, v181
	v_add_f32_e32 v93, v93, v178
	v_add_f32_e32 v94, v94, v179
	v_cvt_pk_bf16_f32 v80, v154, v155
	v_cvt_pk_bf16_f32 v81, v152, v153
	v_cvt_pk_bf16_f32 v82, v180, v181
	v_cvt_pk_bf16_f32 v83, v178, v179
	v_exp_f32_e32 v176, v176
	s_waitcnt lgkmcnt(6)
	v_mfma_f32_32x32x16_bf16 v[48:63], v[64:67], v[80:83], v[48:63]
	ds_read_b64_tr_b16 v[64:65], v198 offset:28672
	ds_read_b64_tr_b16 v[66:67], v198 offset:30720
	v_exp_f32_e32 v177, v177
	v_exp_f32_e32 v172, v172
	s_waitcnt lgkmcnt(6)
	v_mfma_f32_32x32x16_bf16 v[32:47], v[68:71], v[80:83], v[32:47]
	ds_read_b64_tr_b16 v[68:69], v198 offset:29184
	ds_read_b64_tr_b16 v[70:71], v198 offset:31232
	v_exp_f32_e32 v173, v173
	v_exp_f32_e32 v168, v168
	s_waitcnt lgkmcnt(6)
	v_mfma_f32_32x32x16_bf16 v[16:31], v[72:75], v[80:83], v[16:31]
	ds_read_b64_tr_b16 v[72:73], v198 offset:29696
	ds_read_b64_tr_b16 v[74:75], v198 offset:31744
	v_exp_f32_e32 v169, v169
	v_exp_f32_e32 v164, v164
	s_waitcnt lgkmcnt(6)
	v_mfma_f32_32x32x16_bf16 v[0:15], v[76:79], v[80:83], v[0:15]
	ds_read_b64_tr_b16 v[76:77], v198 offset:30208
	ds_read_b64_tr_b16 v[78:79], v198 offset:32256
	v_exp_f32_e32 v165, v165
	s_nop 0
	v_add_f32_e32 v93, v93, v176
	v_add_f32_e32 v94, v94, v177
	v_add_f32_e32 v93, v93, v172
	v_add_f32_e32 v94, v94, v173
	v_add_f32_e32 v93, v93, v168
	v_add_f32_e32 v94, v94, v169
	v_add_f32_e32 v93, v93, v164
	v_add_f32_e32 v94, v94, v165
	v_cvt_pk_bf16_f32 v84, v176, v177
	v_cvt_pk_bf16_f32 v85, v172, v173
	v_cvt_pk_bf16_f32 v86, v168, v169
	v_cvt_pk_bf16_f32 v87, v164, v165
	v_add_f32_e32 v93, v93, v94
	v_fmac_f32_e32 v93, v190, v88
	s_waitcnt lgkmcnt(6)
	v_mfma_f32_32x32x16_bf16 v[48:63], v[64:67], v[84:87], v[48:63]
	s_waitcnt lgkmcnt(4)
	v_mfma_f32_32x32x16_bf16 v[32:47], v[68:71], v[84:87], v[32:47]
	s_waitcnt lgkmcnt(2)
	v_mfma_f32_32x32x16_bf16 v[16:31], v[72:75], v[84:87], v[16:31]
	s_waitcnt lgkmcnt(0)
	v_mfma_f32_32x32x16_bf16 v[0:15], v[76:79], v[84:87], v[0:15]
	v_mov_b32_e32 v190, v93
	v_mov_b32_e32 v192, v90
	s_mov_b64 s[6:7], -1
	s_and_b64 vcc, exec, s[14:15]
	s_cbranch_vccz .LBB0_596

; template <bool MLA>
; DI void attn_unit(LAS unsigned char* lds, const bf16* Qp, int qstride, const bf16* Kp, int kstride, const bf16* KRp, const bf16* Vp, int vstride,
;                   bf16* Op, int ostride, int t_lo, int t_hi, int qc, bool active, int wave, int lane) {
;     ...
;             float mx = s0[0];
; #pragma unroll
;             for (int i = 1; i < 16; ++i) mx = fmaxf(mx, s0[i]);
; #pragma unroll
;             for (int i = 0; i < 16; ++i) mx = fmaxf(mx, s1[i]);
;             mx = fmaxf(mx, __shfl_xor(mx, 32));
;             const float m_new = fmaxf(m_run, mx);
;             const float alpha = __builtin_amdgcn_exp2f(m_run - m_new);
;             m_run = m_new;
;             float ps = 0.f;
; #pragma unroll
;             for (int i = 0; i < 16; ++i) { s0[i] = __builtin_amdgcn_exp2f(s0[i] - m_new); s1[i] = __builtin_amdgcn_exp2f(s1[i] - m_new); ps += s0[i] + s1[i]; }
;             l_run = l_run * alpha + ps;
; #pragma unroll
;             for (int d = 0; d < 4; ++d)
; #pragma unroll
;                 for (int i = 0; i < 16; ++i) o[d][i] *= alpha;
.LBB0_856:
	v_add_u32_e32 v249, s95, v237
	ds_read_b64_tr_b16 v[2:3], v249 offset:16384
	ds_read_b64_tr_b16 v[4:5], v249 offset:18432
	ds_read_b64_tr_b16 v[6:7], v249 offset:16896
	ds_read_b64_tr_b16 v[8:9], v249 offset:18944
	ds_read_b64_tr_b16 v[10:11], v249 offset:17408
	ds_read_b64_tr_b16 v[12:13], v249 offset:19456
	ds_read_b64_tr_b16 v[224:225], v249 offset:17920
	ds_read_b64_tr_b16 v[226:227], v249 offset:19968
	v_max3_f32 v245, v80, v81, v82
	v_max3_f32 v247, v83, v84, v85
	v_max3_f32 v245, v245, v86, v87
	v_max3_f32 v247, v247, v88, v89
	v_max3_f32 v245, v245, v90, v91
	v_max3_f32 v247, v247, v92, v93
	v_max3_f32 v245, v245, v94, v95
	v_max3_f32 v247, v247, v96, v97
	v_max3_f32 v245, v245, v98, v99
	v_max3_f32 v247, v247, v100, v101
	v_max3_f32 v245, v245, v102, v103
	v_max3_f32 v247, v247, v104, v105
	v_max3_f32 v245, v245, v106, v107
	v_max3_f32 v247, v247, v108, v109
	v_max3_f32 v245, v245, v110, v111
	v_max_f32_e32 v245, v245, v247
	v_mov_b32_e32 v247, v245
	s_nop 1
	v_permlane32_swap_b32_e32 v245, v247
	s_nop 0
	v_max3_f32 v243, v244, v245, v247
	v_sub_f32_e32 v246, v244, v243
	v_cmp_gt_f32_e32 vcc, 0xc1000000, v246
	s_cbranch_vccnz .Lresc_mla
	v_mov_b32_e32 v243, v244
	v_mov_b32_e32 v246, 1.0
	s_branch .Lresc_done_mla
.Lresc_mla:
	v_exp_f32_e32 v246, v246
	s_nop 0
	v_pk_mul_f32 v[64:65], v[64:65], v[246:247] op_sel_hi:[1,0]
	v_pk_mul_f32 v[66:67], v[66:67], v[246:247] op_sel_hi:[1,0]
	v_pk_mul_f32 v[68:69], v[68:69], v[246:247] op_sel_hi:[1,0]
	v_pk_mul_f32 v[70:71], v[70:71], v[246:247] op_sel_hi:[1,0]
	v_pk_mul_f32 v[72:73], v[72:73], v[246:247] op_sel_hi:[1,0]
	v_pk_mul_f32 v[74:75], v[74:75], v[246:247] op_sel_hi:[1,0]
	v_pk_mul_f32 v[76:77], v[76:77], v[246:247] op_sel_hi:[1,0]
	v_pk_mul_f32 v[78:79], v[78:79], v[246:247] op_sel_hi:[1,0]
	v_pk_mul_f32 v[48:49], v[48:49], v[246:247] op_sel_hi:[1,0]
	v_pk_mul_f32 v[50:51], v[50:51], v[246:247] op_sel_hi:[1,0]
	v_pk_mul_f32 v[52:53], v[52:53], v[246:247] op_sel_hi:[1,0]
	v_pk_mul_f32 v[54:55], v[54:55], v[246:247] op_sel_hi:[1,0]
	v_pk_mul_f32 v[56:57], v[56:57], v[246:247] op_sel_hi:[1,0]
	v_pk_mul_f32 v[58:59], v[58:59], v[246:247] op_sel_hi:[1,0]
	v_pk_mul_f32 v[60:61], v[60:61], v[246:247] op_sel_hi:[1,0]
	v_pk_mul_f32 v[62:63], v[62:63], v[246:247] op_sel_hi:[1,0]
	v_pk_mul_f32 v[32:33], v[32:33], v[246:247] op_sel_hi:[1,0]
	v_pk_mul_f32 v[34:35], v[34:35], v[246:247] op_sel_hi:[1,0]
	v_pk_mul_f32 v[36:37], v[36:37], v[246:247] op_sel_hi:[1,0]
	v_pk_mul_f32 v[38:39], v[38:39], v[246:247] op_sel_hi:[1,0]
	v_pk_mul_f32 v[40:41], v[40:41], v[246:247] op_sel_hi:[1,0]
	v_pk_mul_f32 v[42:43], v[42:43], v[246:247] op_sel_hi:[1,0]
	v_pk_mul_f32 v[44:45], v[44:45], v[246:247] op_sel_hi:[1,0]
	v_pk_mul_f32 v[46:47], v[46:47], v[246:247] op_sel_hi:[1,0]
	v_pk_mul_f32 v[16:17], v[16:17], v[246:247] op_sel_hi:[1,0]
	v_pk_mul_f32 v[18:19], v[18:19], v[246:247] op_sel_hi:[1,0]
	v_pk_mul_f32 v[20:21], v[20:21], v[246:247] op_sel_hi:[1,0]
	v_pk_mul_f32 v[22:23], v[22:23], v[246:247] op_sel_hi:[1,0]
	v_pk_mul_f32 v[24:25], v[24:25], v[246:247] op_sel_hi:[1,0]
	v_pk_mul_f32 v[26:27], v[26:27], v[246:247] op_sel_hi:[1,0]
	v_pk_mul_f32 v[28:29], v[28:29], v[246:247] op_sel_hi:[1,0]
	v_pk_mul_f32 v[30:31], v[30:31], v[246:247] op_sel_hi:[1,0]
; DI unsigned pk2(float lo, float hi) { f32x2_t v = {lo, hi}; bf16x2_t b = __builtin_convertvector(v, bf16x2_t); return __builtin_bit_cast(unsigned, b); }
; #define MFMA32(a, b, c) __builtin_amdgcn_mfma_f32_32x32x16_bf16((a), (b), (c), 0, 0, 0)
; DI s16x4 vtr(const LAS unsigned char* p) { return __builtin_bit_cast(s16x4, __builtin_amdgcn_ds_read_tr16_b64_v4i16((LAS v4i16_t*)p)); }
; template <bool MLA>
; DI void attn_unit(LAS unsigned char* lds, const bf16* Qp, int qstride, const bf16* Kp, int kstride, const bf16* KRp, const bf16* Vp, int vstride,
;                   bf16* Op, int ostride, int t_lo, int t_hi, int qc, bool active, int wave, int lane) {
;     ...
;             float ps = 0.f;
; #pragma unroll
;             for (int i = 0; i < 16; ++i) { s0[i] = __builtin_amdgcn_exp2f(s0[i] - m_new); s1[i] = __builtin_amdgcn_exp2f(s1[i] - m_new); ps += s0[i] + s1[i]; }
;             l_run = l_run * alpha + ps;
; #pragma unroll
;             for (int d = 0; d < 4; ++d)
; #pragma unroll
;                 for (int i = 0; i < 16; ++i) o[d][i] *= alpha;
; #pragma unroll
;             for (int kt = 0; kt < 2; ++kt) {
; #pragma unroll
;                 for (int s = 0; s < 2; ++s) {
;                     u32x4 pw;
;                     if (kt == 0) { pw.x = pk2(s0[8 * s], s0[8 * s + 1]); pw.y = pk2(s0[8 * s + 2], s0[8 * s + 3]); pw.z = pk2(s0[8 * s + 4], s0[8 * s + 5]); pw.w = pk2(s0[8 * s + 6], s0[8 * s + 7]); }
;                     else { pw.x = pk2(s1[8 * s], s1[8 * s + 1]); pw.y = pk2(s1[8 * s + 2], s1[8 * s + 3]); pw.z = pk2(s1[8 * s + 4], s1[8 * s + 5]); pw.w = pk2(s1[8 * s + 6], s1[8 * s + 7]); }
;                     const bf16x8 pb = __builtin_bit_cast(bf16x8, pw);
; #pragma unroll
;                     for (int dt = 0; dt < 4; ++dt) {
;                         const s16x4 lo = vtr(buf + AT_V + ((4 * kt + 2 * s) * 4 + dt) * 512 + voff);
;                         const s16x4 hi = vtr(buf + AT_V + ((4 * kt + 2 * s + 1) * 4 + dt) * 512 + voff);
;                         const bf16x8 va = __builtin_shufflevector(lo, hi, 0, 1, 2, 3, 4, 5, 6, 7);
;                         o[dt] = MFMA32(va, pb, o[dt]);
;                     }
;                     __builtin_amdgcn_sched_barrier(0);
;                 }
;             }
.Lresc_done_mla:
	v_sub_f32_e32 v80, v80, v243
	v_sub_f32_e32 v81, v81, v243
	v_sub_f32_e32 v82, v82, v243
	v_sub_f32_e32 v83, v83, v243
	v_sub_f32_e32 v84, v84, v243
	v_sub_f32_e32 v85, v85, v243
	v_sub_f32_e32 v86, v86, v243
	v_sub_f32_e32 v87, v87, v243
	v_exp_f32_e32 v80, v80
	v_exp_f32_e32 v81, v81
	v_exp_f32_e32 v82, v82
	v_exp_f32_e32 v83, v83
	v_exp_f32_e32 v84, v84
	v_exp_f32_e32 v85, v85
	v_exp_f32_e32 v86, v86
	v_exp_f32_e32 v87, v87
	v_add_f32_e32 v248, v80, v81
	v_add_f32_e32 v250, v82, v83
	v_add_f32_e32 v248, v248, v84
	v_add_f32_e32 v250, v250, v85
	v_add_f32_e32 v248, v248, v86
	v_add_f32_e32 v250, v250, v87
	v_cvt_pk_bf16_f32 v80, v80, v81
	v_cvt_pk_bf16_f32 v81, v82, v83
	v_cvt_pk_bf16_f32 v82, v84, v85
	v_cvt_pk_bf16_f32 v83, v86, v87
	s_nop 0
	v_sub_f32_e32 v88, v88, v243
	v_sub_f32_e32 v89, v89, v243
	v_sub_f32_e32 v90, v90, v243
	v_sub_f32_e32 v91, v91, v243
	v_sub_f32_e32 v92, v92, v243
	v_sub_f32_e32 v93, v93, v243
	v_sub_f32_e32 v94, v94, v243
	v_sub_f32_e32 v95, v95, v243
	s_waitcnt lgkmcnt(6)
	v_mfma_f32_32x32x16_bf16 v[64:79], v[2:5], v[80:83], v[64:79]
	ds_read_b64_tr_b16 v[2:3], v249 offset:20480
	ds_read_b64_tr_b16 v[4:5], v249 offset:22528
	v_exp_f32_e32 v88, v88
	v_exp_f32_e32 v89, v89
	s_waitcnt lgkmcnt(6)
	v_mfma_f32_32x32x16_bf16 v[48:63], v[6:9], v[80:83], v[48:63]
	ds_read_b64_tr_b16 v[6:7], v249 offset:20992
	ds_read_b64_tr_b16 v[8:9], v249 offset:23040
	v_exp_f32_e32 v90, v90
	v_exp_f32_e32 v91, v91
	s_waitcnt lgkmcnt(6)
	v_mfma_f32_32x32x16_bf16 v[32:47], v[10:13], v[80:83], v[32:47]
	ds_read_b64_tr_b16 v[10:11], v249 offset:21504
	ds_read_b64_tr_b16 v[12:13], v249 offset:23552
	v_exp_f32_e32 v92, v92
	v_exp_f32_e32 v93, v93
	s_waitcnt lgkmcnt(6)
	v_mfma_f32_32x32x16_bf16 v[16:31], v[224:227], v[80:83], v[16:31]
	ds_read_b64_tr_b16 v[224:225], v249 offset:22016
	ds_read_b64_tr_b16 v[226:227], v249 offset:24064
	v_exp_f32_e32 v94, v94
	v_exp_f32_e32 v95, v95
	v_sub_f32_e32 v96, v96, v243
	v_sub_f32_e32 v97, v97, v243
	v_sub_f32_e32 v98, v98, v243
	v_sub_f32_e32 v99, v99, v243
	v_sub_f32_e32 v100, v100, v243
	v_sub_f32_e32 v101, v101, v243
	v_sub_f32_e32 v102, v102, v243
	v_sub_f32_e32 v103, v103, v243
	v_add_f32_e32 v248, v248, v88
	v_add_f32_e32 v250, v250, v89
	v_add_f32_e32 v248, v248, v90
	v_add_f32_e32 v250, v250, v91
	v_add_f32_e32 v248, v248, v92
	v_add_f32_e32 v250, v250, v93
	v_add_f32_e32 v248, v248, v94
	v_add_f32_e32 v250, v250, v95
	v_cvt_pk_bf16_f32 v88, v88, v89
	v_cvt_pk_bf16_f32 v89, v90, v91
	v_cvt_pk_bf16_f32 v90, v92, v93
	v_cvt_pk_bf16_f32 v91, v94, v95
	v_exp_f32_e32 v96, v96
	s_waitcnt lgkmcnt(6)
	v_mfma_f32_32x32x16_bf16 v[64:79], v[2:5], v[88:91], v[64:79]
	ds_read_b64_tr_b16 v[2:3], v249 offset:24576
	ds_read_b64_tr_b16 v[4:5], v249 offset:26624
	v_exp_f32_e32 v97, v97
	v_exp_f32_e32 v98, v98
	s_waitcnt lgkmcnt(6)
	v_mfma_f32_32x32x16_bf16 v[48:63], v[6:9], v[88:91], v[48:63]
	ds_read_b64_tr_b16 v[6:7], v249 offset:25088
	ds_read_b64_tr_b16 v[8:9], v249 offset:27136
	v_exp_f32_e32 v99, v99
	v_exp_f32_e32 v100, v100
	s_waitcnt lgkmcnt(6)
	v_mfma_f32_32x32x16_bf16 v[32:47], v[10:13], v[88:91], v[32:47]
	ds_read_b64_tr_b16 v[10:11], v249 offset:25600
	ds_read_b64_tr_b16 v[12:13], v249 offset:27648
	v_exp_f32_e32 v101, v101
	v_exp_f32_e32 v102, v102
	s_waitcnt lgkmcnt(6)
	v_mfma_f32_32x32x16_bf16 v[16:31], v[224:227], v[88:91], v[16:31]
	ds_read_b64_tr_b16 v[224:225], v249 offset:26112
	ds_read_b64_tr_b16 v[226:227], v249 offset:28160
	v_exp_f32_e32 v103, v103
	v_sub_f32_e32 v104, v104, v243
	v_sub_f32_e32 v105, v105, v243
	v_sub_f32_e32 v106, v106, v243
	v_sub_f32_e32 v107, v107, v243
	v_sub_f32_e32 v108, v108, v243
	v_sub_f32_e32 v109, v109, v243
	v_sub_f32_e32 v110, v110, v243
	v_sub_f32_e32 v111, v111, v243
	v_add_f32_e32 v248, v248, v96
	v_add_f32_e32 v250, v250, v97
	v_add_f32_e32 v248, v248, v98
	v_add_f32_e32 v250, v250, v99
	v_add_f32_e32 v248, v248, v100
	v_add_f32_e32 v250, v250, v101
	v_add_f32_e32 v248, v248, v102
	v_add_f32_e32 v250, v250, v103
	v_cvt_pk_bf16_f32 v96, v96, v97
	v_cvt_pk_bf16_f32 v97, v98, v99
	v_cvt_pk_bf16_f32 v98, v100, v101
	v_cvt_pk_bf16_f32 v99, v102, v103
	v_exp_f32_e32 v104, v104
	s_waitcnt lgkmcnt(6)
	v_mfma_f32_32x32x16_bf16 v[64:79], v[2:5], v[96:99], v[64:79]
	ds_read_b64_tr_b16 v[2:3], v249 offset:28672
	ds_read_b64_tr_b16 v[4:5], v249 offset:30720
	v_exp_f32_e32 v105, v105
	v_exp_f32_e32 v106, v106
	s_waitcnt lgkmcnt(6)
	v_mfma_f32_32x32x16_bf16 v[48:63], v[6:9], v[96:99], v[48:63]
	ds_read_b64_tr_b16 v[6:7], v249 offset:29184
	ds_read_b64_tr_b16 v[8:9], v249 offset:31232
	v_exp_f32_e32 v107, v107
	v_exp_f32_e32 v108, v108
	s_waitcnt lgkmcnt(6)
	v_mfma_f32_32x32x16_bf16 v[32:47], v[10:13], v[96:99], v[32:47]
	ds_read_b64_tr_b16 v[10:11], v249 offset:29696
	ds_read_b64_tr_b16 v[12:13], v249 offset:31744
	v_exp_f32_e32 v109, v109
	v_exp_f32_e32 v110, v110
	s_waitcnt lgkmcnt(6)
	v_mfma_f32_32x32x16_bf16 v[16:31], v[224:227], v[96:99], v[16:31]
	ds_read_b64_tr_b16 v[224:225], v249 offset:30208
	ds_read_b64_tr_b16 v[226:227], v249 offset:32256
	v_exp_f32_e32 v111, v111
	s_nop 0
	v_add_f32_e32 v248, v248, v104
	v_add_f32_e32 v250, v250, v105
	v_add_f32_e32 v248, v248, v106
	v_add_f32_e32 v250, v250, v107
	v_add_f32_e32 v248, v248, v108
	v_add_f32_e32 v250, v250, v109
	v_add_f32_e32 v248, v248, v110
	v_add_f32_e32 v250, v250, v111
	v_cvt_pk_bf16_f32 v104, v104, v105
	v_cvt_pk_bf16_f32 v105, v106, v107
	v_cvt_pk_bf16_f32 v106, v108, v109
	v_cvt_pk_bf16_f32 v107, v110, v111
	v_add_f32_e32 v248, v248, v250
	v_fmac_f32_e32 v248, v242, v246
	s_waitcnt lgkmcnt(6)
	v_mfma_f32_32x32x16_bf16 v[64:79], v[2:5], v[104:107], v[64:79]
	s_waitcnt lgkmcnt(4)
	v_mfma_f32_32x32x16_bf16 v[48:63], v[6:9], v[104:107], v[48:63]
	s_waitcnt lgkmcnt(2)
	v_mfma_f32_32x32x16_bf16 v[32:47], v[10:13], v[104:107], v[32:47]
	s_waitcnt lgkmcnt(0)
	v_mfma_f32_32x32x16_bf16 v[16:31], v[224:227], v[104:107], v[16:31]
	v_mov_b32_e32 v242, v248
	v_mov_b32_e32 v244, v243
	s_mov_b64 s[58:59], -1
	s_and_b64 vcc, exec, s[12:13]
	s_cbranch_vccz .LBB0_854

; DI void unpack8(u32x4 w, float* f) { f[0] = bflo(w.x); f[1] = bfhi(w.x); f[2] = bflo(w.y); f[3] = bfhi(w.y); f[4] = bflo(w.z); f[5] = bfhi(w.z); f[6] = bflo(w.w); f[7] = bfhi(w.w); }
; DI u32x4 pack8(const float* f) { u32x4 w; w.x = pk2(f[0], f[1]); w.y = pk2(f[2], f[3]); w.z = pk2(f[4], f[5]); w.w = pk2(f[6], f[7]); return w; }
;     DI void operator()(AccRef acc, const Unit& u, int wr, int wc, int fr, int fq) const {
;         const int col0 = u.pn * 256 + wc * 32 + 8 * fq;
;         const int row0 = u.pm * 256 + wr * 64 + fr;
; #pragma unroll
;         for (int ai = 0; ai < 2; ++ai)
; #pragma unroll
;             for (int m = 0; m < 4; ++m) {
; #pragma unroll
;                 for (int bj = 0; bj < 2; ++bj) {
;                     const size_t o = (size_t)(row0 + ai * 128 + m * 16) * 2048 + col0 + bj * 128;
;                     const pg8::f32x4 v0 = acc[ai][bj][m][0], v1 = acc[ai][bj][m][1];
;                     float g[8], r[8]; unpack8_u8(*(const u32x2*)(G + o), g);
;                     r[0] = g[0] * v0[0]; r[1] = g[1] * v0[1]; r[2] = g[2] * v0[2]; r[3] = g[3] * v0[3];
;                     r[4] = g[4] * v1[0]; r[5] = g[5] * v1[1]; r[6] = g[6] * v1[2]; r[7] = g[7] * v1[3];
;                     if (add) { float t[8]; unpack8(*(const u32x4*)(MIX + o), t);
; #pragma unroll
;                         for (int j = 0; j < 8; ++j) r[j] += t[j]; }
;                     *(u32x4*)(MIX + o) = pack8(r);
;                 }
;             }
;     }
.LBB0_961:
	v_lshl_add_u32 v150, s62, 8, v129
	v_lshl_or_b32 v148, s83, 8, v153
	v_ashrrev_i32_e32 v151, 31, v150
	v_ashrrev_i32_e32 v149, 31, v148
	v_lshlrev_b64 v[146:147], 11, v[150:151]
	v_lshl_add_u64 v[146:147], v[146:147], 0, v[148:149]
	s_mov_b32 s98, 0x8000
	s_mov_b32 s99, 0
	s_mov_b32 s100, 0x28000
	s_mov_b32 s101, 0
	v_lshl_add_u64 v[208:209], s[6:7], 0, v[146:147]
	global_load_dwordx2 v[176:177], v[208:209], off
	global_load_dwordx2 v[178:179], v[208:209], off offset:128
	v_lshl_add_u64 v[208:209], v[208:209], 0, s[98:99]
	global_load_dwordx2 v[180:181], v[208:209], off
	global_load_dwordx2 v[182:183], v[208:209], off offset:128
	v_lshl_add_u64 v[208:209], v[208:209], 0, s[98:99]
	global_load_dwordx2 v[184:185], v[208:209], off
	global_load_dwordx2 v[186:187], v[208:209], off offset:128
	v_lshl_add_u64 v[208:209], v[208:209], 0, s[98:99]
	global_load_dwordx2 v[188:189], v[208:209], off
	global_load_dwordx2 v[190:191], v[208:209], off offset:128
	v_lshl_add_u64 v[208:209], v[208:209], 0, s[100:101]
	global_load_dwordx2 v[192:193], v[208:209], off
	global_load_dwordx2 v[194:195], v[208:209], off offset:128
	v_lshl_add_u64 v[208:209], v[208:209], 0, s[98:99]
	global_load_dwordx2 v[196:197], v[208:209], off
	global_load_dwordx2 v[198:199], v[208:209], off offset:128
	v_lshl_add_u64 v[208:209], v[208:209], 0, s[98:99]
	global_load_dwordx2 v[200:201], v[208:209], off
	global_load_dwordx2 v[202:203], v[208:209], off offset:128
	v_lshl_add_u64 v[208:209], v[208:209], 0, s[98:99]
	global_load_dwordx2 v[204:205], v[208:209], off
	global_load_dwordx2 v[206:207], v[208:209], off offset:128
	v_lshl_add_u64 v[158:159], s[6:7], 0, v[146:147]
	s_nop 0
	v_lshl_add_u64 v[162:163], v[146:147], 1, s[12:13]
	v_or_b32_e32 v164, 0x80, v146
	v_mov_b32_e32 v165, v147
	v_lshl_add_u64 v[166:167], s[6:7], 0, v[164:165]
	s_andn2_b64 vcc, exec, s[2:3]
	s_mov_b64 s[2:3], -1
	s_waitcnt vmcnt(0)
	v_cvt_f32_ubyte1_e32 v169, v176
	v_cvt_f32_ubyte0_e32 v168, v176
	v_cvt_f32_ubyte3_e32 v171, v176
	v_cvt_f32_ubyte2_e32 v170, v176
	v_cvt_f32_ubyte1_e32 v173, v177
	v_cvt_f32_ubyte0_e32 v172, v177
	v_cvt_f32_ubyte3_e32 v175, v177
	v_cvt_f32_ubyte2_e32 v174, v177
	v_pk_mul_f32 v[158:159], v[168:169], s[40:41] op_sel_hi:[1,0]
	v_pk_mul_f32 v[168:169], v[170:171], s[40:41] op_sel_hi:[1,0]
	v_pk_mul_f32 v[170:171], v[172:173], s[40:41] op_sel_hi:[1,0]
	v_pk_mul_f32 v[172:173], v[174:175], s[40:41] op_sel_hi:[1,0]
	v_pk_mul_f32 v[124:125], v[124:125], v[158:159]
	v_pk_mul_f32 v[126:127], v[126:127], v[168:169]
	v_pk_mul_f32 v[158:159], v[120:121], v[170:171]
	v_pk_mul_f32 v[168:169], v[122:123], v[172:173]
	v_cvt_pk_bf16_f32 v120, v124, v125
	v_cvt_pk_bf16_f32 v121, v126, v127
	v_cvt_pk_bf16_f32 v122, v158, v159
	v_cvt_pk_bf16_f32 v123, v168, v169
	global_store_dwordx4 v[162:163], v[120:123], off
	s_nop 0
	v_lshl_add_u64 v[124:125], v[164:165], 1, s[12:13]
	v_or_b32_e32 v122, 16, v150
	v_ashrrev_i32_e32 v123, 31, v122
	v_lshlrev_b64 v[122:123], 11, v[122:123]
	v_lshl_add_u64 v[122:123], v[122:123], 0, v[148:149]
	v_lshl_add_u64 v[126:127], s[6:7], 0, v[122:123]
	v_cvt_f32_ubyte1_e32 v159, v178
	v_cvt_f32_ubyte0_e32 v158, v178
	v_cvt_f32_ubyte3_e32 v163, v178
	v_cvt_f32_ubyte2_e32 v162, v178
	v_cvt_f32_ubyte1_e32 v165, v179
	v_cvt_f32_ubyte0_e32 v164, v179
	v_cvt_f32_ubyte3_e32 v167, v179
	v_cvt_f32_ubyte2_e32 v166, v179
	v_pk_mul_f32 v[120:121], v[158:159], s[40:41] op_sel_hi:[1,0]
	v_pk_mul_f32 v[158:159], v[162:163], s[40:41] op_sel_hi:[1,0]
	v_pk_mul_f32 v[162:163], v[164:165], s[40:41] op_sel_hi:[1,0]
	v_pk_mul_f32 v[164:165], v[166:167], s[40:41] op_sel_hi:[1,0]
	v_pk_mul_f32 v[116:117], v[116:117], v[120:121]
	v_pk_mul_f32 v[118:119], v[118:119], v[158:159]
	v_pk_mul_f32 v[120:121], v[112:113], v[162:163]
	v_pk_mul_f32 v[158:159], v[114:115], v[164:165]
	v_cvt_pk_bf16_f32 v112, v116, v117
	v_cvt_pk_bf16_f32 v113, v118, v119
	v_cvt_pk_bf16_f32 v114, v120, v121
	v_cvt_pk_bf16_f32 v115, v158, v159
	global_store_dwordx4 v[124:125], v[112:115], off
	s_nop 0
	v_cvt_f32_ubyte1_e32 v119, v180
	v_cvt_f32_ubyte0_e32 v118, v180
	v_cvt_f32_ubyte3_e32 v121, v180
	v_cvt_f32_ubyte2_e32 v120, v180
	v_cvt_f32_ubyte1_e32 v125, v181
	v_cvt_f32_ubyte0_e32 v124, v181
	v_cvt_f32_ubyte3_e32 v127, v181
	v_cvt_f32_ubyte2_e32 v126, v181
	v_pk_mul_f32 v[112:113], v[118:119], s[40:41] op_sel_hi:[1,0]
	v_pk_mul_f32 v[118:119], v[120:121], s[40:41] op_sel_hi:[1,0]
	v_pk_mul_f32 v[120:121], v[124:125], s[40:41] op_sel_hi:[1,0]
	v_pk_mul_f32 v[124:125], v[126:127], s[40:41] op_sel_hi:[1,0]
	v_pk_mul_f32 v[108:109], v[108:109], v[112:113]
	v_pk_mul_f32 v[110:111], v[110:111], v[118:119]
	v_pk_mul_f32 v[112:113], v[104:105], v[120:121]
	v_pk_mul_f32 v[118:119], v[106:107], v[124:125]
	v_lshl_add_u64 v[114:115], v[122:123], 1, s[12:13]
	v_or_b32_e32 v122, 0x80, v122
	v_cvt_pk_bf16_f32 v104, v108, v109
	v_cvt_pk_bf16_f32 v105, v110, v111
	v_cvt_pk_bf16_f32 v106, v112, v113
	v_cvt_pk_bf16_f32 v107, v118, v119
	v_lshl_add_u64 v[116:117], s[6:7], 0, v[122:123]
	global_store_dwordx4 v[114:115], v[104:107], off
	s_nop 0
	v_lshl_add_u64 v[110:111], v[122:123], 1, s[12:13]
	v_or_b32_e32 v106, 32, v150
	v_ashrrev_i32_e32 v107, 31, v106
	v_lshlrev_b64 v[106:107], 11, v[106:107]
	v_lshl_add_u64 v[106:107], v[106:107], 0, v[148:149]
	v_lshl_add_u64 v[108:109], s[6:7], 0, v[106:107]
	v_cvt_f32_ubyte1_e32 v113, v182
	v_cvt_f32_ubyte0_e32 v112, v182
	v_cvt_f32_ubyte3_e32 v115, v182
	v_cvt_f32_ubyte2_e32 v114, v182
	v_cvt_f32_ubyte1_e32 v117, v183
	v_cvt_f32_ubyte0_e32 v116, v183
	v_cvt_f32_ubyte3_e32 v119, v183
	v_cvt_f32_ubyte2_e32 v118, v183
	v_pk_mul_f32 v[104:105], v[112:113], s[40:41] op_sel_hi:[1,0]
; DI void unpack8(u32x4 w, float* f) { f[0] = bflo(w.x); f[1] = bfhi(w.x); f[2] = bflo(w.y); f[3] = bfhi(w.y); f[4] = bflo(w.z); f[5] = bfhi(w.z); f[6] = bflo(w.w); f[7] = bfhi(w.w); }
; DI u32x4 pack8(const float* f) { u32x4 w; w.x = pk2(f[0], f[1]); w.y = pk2(f[2], f[3]); w.z = pk2(f[4], f[5]); w.w = pk2(f[6], f[7]); return w; }
;     DI void operator()(AccRef acc, const Unit& u, int wr, int wc, int fr, int fq) const {
;         const int col0 = u.pn * 256 + wc * 32 + 8 * fq;
;         const int row0 = u.pm * 256 + wr * 64 + fr;
; #pragma unroll
;         for (int ai = 0; ai < 2; ++ai)
; #pragma unroll
;             for (int m = 0; m < 4; ++m) {
; #pragma unroll
;                 for (int bj = 0; bj < 2; ++bj) {
;                     const size_t o = (size_t)(row0 + ai * 128 + m * 16) * 2048 + col0 + bj * 128;
;                     const pg8::f32x4 v0 = acc[ai][bj][m][0], v1 = acc[ai][bj][m][1];
;                     float g[8], r[8]; unpack8_u8(*(const u32x2*)(G + o), g);
;                     r[0] = g[0] * v0[0]; r[1] = g[1] * v0[1]; r[2] = g[2] * v0[2]; r[3] = g[3] * v0[3];
;                     r[4] = g[4] * v1[0]; r[5] = g[5] * v1[1]; r[6] = g[6] * v1[2]; r[7] = g[7] * v1[3];
;                     if (add) { float t[8]; unpack8(*(const u32x4*)(MIX + o), t);
; #pragma unroll
;                         for (int j = 0; j < 8; ++j) r[j] += t[j]; }
;                     *(u32x4*)(MIX + o) = pack8(r);
;                 }
;             }
;     }
	v_pk_mul_f32 v[112:113], v[114:115], s[40:41] op_sel_hi:[1,0]
	v_pk_mul_f32 v[114:115], v[116:117], s[40:41] op_sel_hi:[1,0]
	v_pk_mul_f32 v[116:117], v[118:119], s[40:41] op_sel_hi:[1,0]
	v_pk_mul_f32 v[100:101], v[100:101], v[104:105]
	v_pk_mul_f32 v[102:103], v[102:103], v[112:113]
	v_pk_mul_f32 v[104:105], v[96:97], v[114:115]
	v_pk_mul_f32 v[112:113], v[98:99], v[116:117]
	v_cvt_pk_bf16_f32 v96, v100, v101
	v_cvt_pk_bf16_f32 v97, v102, v103
	v_cvt_pk_bf16_f32 v98, v104, v105
	v_cvt_pk_bf16_f32 v99, v112, v113
	global_store_dwordx4 v[110:111], v[96:99], off
	s_nop 0
	v_cvt_f32_ubyte1_e32 v103, v184
	v_cvt_f32_ubyte0_e32 v102, v184
	v_cvt_f32_ubyte3_e32 v105, v184
	v_cvt_f32_ubyte2_e32 v104, v184
	v_cvt_f32_ubyte1_e32 v109, v185
	v_cvt_f32_ubyte0_e32 v108, v185
	v_cvt_f32_ubyte3_e32 v111, v185
	v_cvt_f32_ubyte2_e32 v110, v185
	v_pk_mul_f32 v[96:97], v[102:103], s[40:41] op_sel_hi:[1,0]
	v_pk_mul_f32 v[102:103], v[104:105], s[40:41] op_sel_hi:[1,0]
	v_pk_mul_f32 v[104:105], v[108:109], s[40:41] op_sel_hi:[1,0]
	v_pk_mul_f32 v[108:109], v[110:111], s[40:41] op_sel_hi:[1,0]
	v_pk_mul_f32 v[92:93], v[92:93], v[96:97]
	v_pk_mul_f32 v[94:95], v[94:95], v[102:103]
	v_pk_mul_f32 v[96:97], v[88:89], v[104:105]
	v_pk_mul_f32 v[102:103], v[90:91], v[108:109]
	v_lshl_add_u64 v[98:99], v[106:107], 1, s[12:13]
	v_or_b32_e32 v106, 0x80, v106
	v_cvt_pk_bf16_f32 v88, v92, v93
	v_cvt_pk_bf16_f32 v89, v94, v95
	v_cvt_pk_bf16_f32 v90, v96, v97
	v_cvt_pk_bf16_f32 v91, v102, v103
	v_lshl_add_u64 v[100:101], s[6:7], 0, v[106:107]
	global_store_dwordx4 v[98:99], v[88:91], off
	s_nop 0
	v_lshl_add_u64 v[94:95], v[106:107], 1, s[12:13]
	v_or_b32_e32 v90, 48, v150
	v_ashrrev_i32_e32 v91, 31, v90
	v_lshlrev_b64 v[90:91], 11, v[90:91]
	v_lshl_add_u64 v[90:91], v[90:91], 0, v[148:149]
	v_lshl_add_u64 v[92:93], s[6:7], 0, v[90:91]
	v_cvt_f32_ubyte1_e32 v97, v186
	v_cvt_f32_ubyte0_e32 v96, v186
	v_cvt_f32_ubyte3_e32 v99, v186
	v_cvt_f32_ubyte2_e32 v98, v186
	v_cvt_f32_ubyte1_e32 v101, v187
	v_cvt_f32_ubyte0_e32 v100, v187
	v_cvt_f32_ubyte3_e32 v103, v187
	v_cvt_f32_ubyte2_e32 v102, v187
	v_pk_mul_f32 v[88:89], v[96:97], s[40:41] op_sel_hi:[1,0]
	v_pk_mul_f32 v[96:97], v[98:99], s[40:41] op_sel_hi:[1,0]
	v_pk_mul_f32 v[98:99], v[100:101], s[40:41] op_sel_hi:[1,0]
	v_pk_mul_f32 v[100:101], v[102:103], s[40:41] op_sel_hi:[1,0]
	v_pk_mul_f32 v[84:85], v[84:85], v[88:89]
	v_pk_mul_f32 v[86:87], v[86:87], v[96:97]
	v_pk_mul_f32 v[88:89], v[80:81], v[98:99]
	v_pk_mul_f32 v[96:97], v[82:83], v[100:101]
	v_cvt_pk_bf16_f32 v80, v84, v85
	v_cvt_pk_bf16_f32 v81, v86, v87
	v_cvt_pk_bf16_f32 v82, v88, v89
	v_cvt_pk_bf16_f32 v83, v96, v97
	global_store_dwordx4 v[94:95], v[80:83], off
	s_nop 0
	v_cvt_f32_ubyte1_e32 v87, v188
	v_cvt_f32_ubyte0_e32 v86, v188
	v_cvt_f32_ubyte3_e32 v89, v188
	v_cvt_f32_ubyte2_e32 v88, v188
	v_cvt_f32_ubyte1_e32 v93, v189
	v_cvt_f32_ubyte0_e32 v92, v189
	v_cvt_f32_ubyte3_e32 v95, v189
	v_cvt_f32_ubyte2_e32 v94, v189
	v_pk_mul_f32 v[80:81], v[86:87], s[40:41] op_sel_hi:[1,0]
	v_pk_mul_f32 v[86:87], v[88:89], s[40:41] op_sel_hi:[1,0]
	v_pk_mul_f32 v[88:89], v[92:93], s[40:41] op_sel_hi:[1,0]
	v_pk_mul_f32 v[92:93], v[94:95], s[40:41] op_sel_hi:[1,0]
	v_pk_mul_f32 v[76:77], v[76:77], v[80:81]
	v_pk_mul_f32 v[78:79], v[78:79], v[86:87]
	v_pk_mul_f32 v[80:81], v[72:73], v[88:89]
	v_pk_mul_f32 v[86:87], v[74:75], v[92:93]
	v_lshl_add_u64 v[82:83], v[90:91], 1, s[12:13]
	v_or_b32_e32 v90, 0x80, v90
	v_cvt_pk_bf16_f32 v72, v76, v77
	v_cvt_pk_bf16_f32 v73, v78, v79
	v_cvt_pk_bf16_f32 v74, v80, v81
	v_cvt_pk_bf16_f32 v75, v86, v87
	v_lshl_add_u64 v[84:85], s[6:7], 0, v[90:91]
	global_store_dwordx4 v[82:83], v[72:75], off
	s_nop 0
	v_lshl_add_u64 v[78:79], v[90:91], 1, s[12:13]
	v_lshl_add_u64 v[74:75], v[146:147], 0, s[0:1]
	v_lshl_add_u64 v[76:77], s[6:7], 0, v[74:75]
	v_cvt_f32_ubyte1_e32 v81, v190
	v_cvt_f32_ubyte0_e32 v80, v190
	v_cvt_f32_ubyte3_e32 v83, v190
	v_cvt_f32_ubyte2_e32 v82, v190
	v_cvt_f32_ubyte1_e32 v85, v191
	v_cvt_f32_ubyte0_e32 v84, v191
	v_cvt_f32_ubyte3_e32 v87, v191
	v_cvt_f32_ubyte2_e32 v86, v191
	v_pk_mul_f32 v[72:73], v[80:81], s[40:41] op_sel_hi:[1,0]
	v_pk_mul_f32 v[80:81], v[82:83], s[40:41] op_sel_hi:[1,0]
	v_pk_mul_f32 v[82:83], v[84:85], s[40:41] op_sel_hi:[1,0]
	v_pk_mul_f32 v[84:85], v[86:87], s[40:41] op_sel_hi:[1,0]
	v_pk_mul_f32 v[68:69], v[68:69], v[72:73]
	v_pk_mul_f32 v[70:71], v[70:71], v[80:81]
	v_pk_mul_f32 v[72:73], v[64:65], v[82:83]
	v_pk_mul_f32 v[80:81], v[66:67], v[84:85]
	v_cvt_pk_bf16_f32 v64, v68, v69
	v_cvt_pk_bf16_f32 v65, v70, v71
	v_cvt_pk_bf16_f32 v66, v72, v73
	v_cvt_pk_bf16_f32 v67, v80, v81
	global_store_dwordx4 v[78:79], v[64:67], off
	s_nop 0
	v_lshl_add_u64 v[68:69], v[74:75], 1, s[12:13]
	v_lshl_add_u64 v[66:67], v[146:147], 0, s[16:17]
	v_lshl_add_u64 v[70:71], s[6:7], 0, v[66:67]
	v_cvt_f32_ubyte1_e32 v73, v192
	v_cvt_f32_ubyte0_e32 v72, v192
	v_cvt_f32_ubyte3_e32 v75, v192
	v_cvt_f32_ubyte2_e32 v74, v192
	v_cvt_f32_ubyte1_e32 v77, v193
	v_cvt_f32_ubyte0_e32 v76, v193
	v_cvt_f32_ubyte3_e32 v79, v193
	v_cvt_f32_ubyte2_e32 v78, v193
	v_pk_mul_f32 v[64:65], v[72:73], s[40:41] op_sel_hi:[1,0]
	v_pk_mul_f32 v[72:73], v[74:75], s[40:41] op_sel_hi:[1,0]
	v_pk_mul_f32 v[74:75], v[76:77], s[40:41] op_sel_hi:[1,0]
	v_pk_mul_f32 v[76:77], v[78:79], s[40:41] op_sel_hi:[1,0]
	v_pk_mul_f32 v[60:61], v[60:61], v[64:65]
	v_pk_mul_f32 v[62:63], v[62:63], v[72:73]
	v_pk_mul_f32 v[64:65], v[56:57], v[74:75]
	v_pk_mul_f32 v[72:73], v[58:59], v[76:77]
	v_cvt_pk_bf16_f32 v56, v60, v61
	v_cvt_pk_bf16_f32 v57, v62, v63
	v_cvt_pk_bf16_f32 v58, v64, v65
	v_cvt_pk_bf16_f32 v59, v72, v73
	global_store_dwordx4 v[68:69], v[56:59], off
; DI void unpack8(u32x4 w, float* f) { f[0] = bflo(w.x); f[1] = bfhi(w.x); f[2] = bflo(w.y); f[3] = bfhi(w.y); f[4] = bflo(w.z); f[5] = bfhi(w.z); f[6] = bflo(w.w); f[7] = bfhi(w.w); }
; DI u32x4 pack8(const float* f) { u32x4 w; w.x = pk2(f[0], f[1]); w.y = pk2(f[2], f[3]); w.z = pk2(f[4], f[5]); w.w = pk2(f[6], f[7]); return w; }
;     DI void operator()(AccRef acc, const Unit& u, int wr, int wc, int fr, int fq) const {
;         const int col0 = u.pn * 256 + wc * 32 + 8 * fq;
;         const int row0 = u.pm * 256 + wr * 64 + fr;
; #pragma unroll
;         for (int ai = 0; ai < 2; ++ai)
; #pragma unroll
;             for (int m = 0; m < 4; ++m) {
; #pragma unroll
;                 for (int bj = 0; bj < 2; ++bj) {
;                     const size_t o = (size_t)(row0 + ai * 128 + m * 16) * 2048 + col0 + bj * 128;
;                     const pg8::f32x4 v0 = acc[ai][bj][m][0], v1 = acc[ai][bj][m][1];
;                     float g[8], r[8]; unpack8_u8(*(const u32x2*)(G + o), g);
;                     r[0] = g[0] * v0[0]; r[1] = g[1] * v0[1]; r[2] = g[2] * v0[2]; r[3] = g[3] * v0[3];
;                     r[4] = g[4] * v1[0]; r[5] = g[5] * v1[1]; r[6] = g[6] * v1[2]; r[7] = g[7] * v1[3];
;                     if (add) { float t[8]; unpack8(*(const u32x4*)(MIX + o), t);
; #pragma unroll
;                         for (int j = 0; j < 8; ++j) r[j] += t[j]; }
;                     *(u32x4*)(MIX + o) = pack8(r);
;                 }
;             }
;     }
	s_nop 0
	v_lshl_add_u64 v[60:61], v[66:67], 1, s[12:13]
	v_lshl_add_u64 v[58:59], v[146:147], 0, s[42:43]
	v_lshl_add_u64 v[62:63], s[6:7], 0, v[58:59]
	v_cvt_f32_ubyte1_e32 v65, v194
	v_cvt_f32_ubyte0_e32 v64, v194
	v_cvt_f32_ubyte3_e32 v67, v194
	v_cvt_f32_ubyte2_e32 v66, v194
	v_cvt_f32_ubyte1_e32 v69, v195
	v_cvt_f32_ubyte0_e32 v68, v195
	v_cvt_f32_ubyte3_e32 v71, v195
	v_cvt_f32_ubyte2_e32 v70, v195
	v_pk_mul_f32 v[56:57], v[64:65], s[40:41] op_sel_hi:[1,0]
	v_pk_mul_f32 v[64:65], v[66:67], s[40:41] op_sel_hi:[1,0]
	v_pk_mul_f32 v[66:67], v[68:69], s[40:41] op_sel_hi:[1,0]
	v_pk_mul_f32 v[68:69], v[70:71], s[40:41] op_sel_hi:[1,0]
	v_pk_mul_f32 v[52:53], v[52:53], v[56:57]
	v_pk_mul_f32 v[54:55], v[54:55], v[64:65]
	v_pk_mul_f32 v[56:57], v[48:49], v[66:67]
	v_pk_mul_f32 v[64:65], v[50:51], v[68:69]
	v_cvt_pk_bf16_f32 v48, v52, v53
	v_cvt_pk_bf16_f32 v49, v54, v55
	v_cvt_pk_bf16_f32 v50, v56, v57
	v_cvt_pk_bf16_f32 v51, v64, v65
	global_store_dwordx4 v[60:61], v[48:51], off
	s_nop 0
	v_lshl_add_u64 v[52:53], v[58:59], 1, s[12:13]
	v_lshl_add_u64 v[50:51], v[146:147], 0, s[44:45]
	v_lshl_add_u64 v[54:55], s[6:7], 0, v[50:51]
	v_cvt_f32_ubyte1_e32 v57, v196
	v_cvt_f32_ubyte0_e32 v56, v196
	v_cvt_f32_ubyte3_e32 v59, v196
	v_cvt_f32_ubyte2_e32 v58, v196
	v_cvt_f32_ubyte1_e32 v61, v197
	v_cvt_f32_ubyte0_e32 v60, v197
	v_cvt_f32_ubyte3_e32 v63, v197
	v_cvt_f32_ubyte2_e32 v62, v197
	v_pk_mul_f32 v[48:49], v[56:57], s[40:41] op_sel_hi:[1,0]
	v_pk_mul_f32 v[56:57], v[58:59], s[40:41] op_sel_hi:[1,0]
	v_pk_mul_f32 v[58:59], v[60:61], s[40:41] op_sel_hi:[1,0]
	v_pk_mul_f32 v[60:61], v[62:63], s[40:41] op_sel_hi:[1,0]
	v_pk_mul_f32 v[44:45], v[44:45], v[48:49]
	v_pk_mul_f32 v[46:47], v[46:47], v[56:57]
	v_pk_mul_f32 v[48:49], v[40:41], v[58:59]
	v_pk_mul_f32 v[56:57], v[42:43], v[60:61]
	v_cvt_pk_bf16_f32 v40, v44, v45
	v_cvt_pk_bf16_f32 v41, v46, v47
	v_cvt_pk_bf16_f32 v42, v48, v49
	v_cvt_pk_bf16_f32 v43, v56, v57
	global_store_dwordx4 v[52:53], v[40:43], off
	s_nop 0
	v_lshl_add_u64 v[44:45], v[50:51], 1, s[12:13]
	v_lshl_add_u64 v[42:43], v[146:147], 0, s[46:47]
	v_lshl_add_u64 v[46:47], s[6:7], 0, v[42:43]
	v_cvt_f32_ubyte1_e32 v49, v198
	v_cvt_f32_ubyte0_e32 v48, v198
	v_cvt_f32_ubyte3_e32 v51, v198
	v_cvt_f32_ubyte2_e32 v50, v198
	v_cvt_f32_ubyte1_e32 v53, v199
	v_cvt_f32_ubyte0_e32 v52, v199
	v_cvt_f32_ubyte3_e32 v55, v199
	v_cvt_f32_ubyte2_e32 v54, v199
	v_pk_mul_f32 v[40:41], v[48:49], s[40:41] op_sel_hi:[1,0]
	v_pk_mul_f32 v[48:49], v[50:51], s[40:41] op_sel_hi:[1,0]
	v_pk_mul_f32 v[50:51], v[52:53], s[40:41] op_sel_hi:[1,0]
	v_pk_mul_f32 v[52:53], v[54:55], s[40:41] op_sel_hi:[1,0]
	v_pk_mul_f32 v[36:37], v[36:37], v[40:41]
	v_pk_mul_f32 v[38:39], v[38:39], v[48:49]
	v_pk_mul_f32 v[40:41], v[32:33], v[50:51]
	v_pk_mul_f32 v[48:49], v[34:35], v[52:53]
	v_cvt_pk_bf16_f32 v32, v36, v37
	v_cvt_pk_bf16_f32 v33, v38, v39
	v_cvt_pk_bf16_f32 v34, v40, v41
	v_cvt_pk_bf16_f32 v35, v48, v49
	global_store_dwordx4 v[44:45], v[32:35], off
	s_nop 0
	v_lshl_add_u64 v[36:37], v[42:43], 1, s[12:13]
	v_lshl_add_u64 v[34:35], v[146:147], 0, s[48:49]
	v_lshl_add_u64 v[38:39], s[6:7], 0, v[34:35]
	v_cvt_f32_ubyte1_e32 v41, v200
	v_cvt_f32_ubyte0_e32 v40, v200
	v_cvt_f32_ubyte3_e32 v43, v200
	v_cvt_f32_ubyte2_e32 v42, v200
	v_cvt_f32_ubyte1_e32 v45, v201
	v_cvt_f32_ubyte0_e32 v44, v201
	v_cvt_f32_ubyte3_e32 v47, v201
	v_cvt_f32_ubyte2_e32 v46, v201
	v_pk_mul_f32 v[32:33], v[40:41], s[40:41] op_sel_hi:[1,0]
	v_pk_mul_f32 v[40:41], v[42:43], s[40:41] op_sel_hi:[1,0]
	v_pk_mul_f32 v[42:43], v[44:45], s[40:41] op_sel_hi:[1,0]
	v_pk_mul_f32 v[44:45], v[46:47], s[40:41] op_sel_hi:[1,0]
	v_pk_mul_f32 v[28:29], v[28:29], v[32:33]
	v_pk_mul_f32 v[30:31], v[30:31], v[40:41]
	v_pk_mul_f32 v[32:33], v[24:25], v[42:43]
	v_pk_mul_f32 v[40:41], v[26:27], v[44:45]
	v_cvt_pk_bf16_f32 v24, v28, v29
	v_cvt_pk_bf16_f32 v25, v30, v31
	v_cvt_pk_bf16_f32 v26, v32, v33
	v_cvt_pk_bf16_f32 v27, v40, v41
	global_store_dwordx4 v[36:37], v[24:27], off
	s_nop 0
	v_lshl_add_u64 v[28:29], v[34:35], 1, s[12:13]
	v_lshl_add_u64 v[26:27], v[146:147], 0, s[50:51]
	v_lshl_add_u64 v[30:31], s[6:7], 0, v[26:27]
	v_cvt_f32_ubyte1_e32 v33, v202
	v_cvt_f32_ubyte0_e32 v32, v202
	v_cvt_f32_ubyte3_e32 v35, v202
	v_cvt_f32_ubyte2_e32 v34, v202
	v_cvt_f32_ubyte1_e32 v37, v203
	v_cvt_f32_ubyte0_e32 v36, v203
	v_cvt_f32_ubyte3_e32 v39, v203
	v_cvt_f32_ubyte2_e32 v38, v203
	v_pk_mul_f32 v[24:25], v[32:33], s[40:41] op_sel_hi:[1,0]
	v_pk_mul_f32 v[32:33], v[34:35], s[40:41] op_sel_hi:[1,0]
	v_pk_mul_f32 v[34:35], v[36:37], s[40:41] op_sel_hi:[1,0]
	v_pk_mul_f32 v[36:37], v[38:39], s[40:41] op_sel_hi:[1,0]
	v_pk_mul_f32 v[20:21], v[20:21], v[24:25]
	v_pk_mul_f32 v[22:23], v[22:23], v[32:33]
	v_pk_mul_f32 v[24:25], v[16:17], v[34:35]
	v_pk_mul_f32 v[32:33], v[18:19], v[36:37]
	v_cvt_pk_bf16_f32 v16, v20, v21
	v_cvt_pk_bf16_f32 v17, v22, v23
	v_cvt_pk_bf16_f32 v18, v24, v25
	v_cvt_pk_bf16_f32 v19, v32, v33
	global_store_dwordx4 v[28:29], v[16:19], off
	s_nop 0
	v_lshl_add_u64 v[20:21], v[26:27], 1, s[12:13]
	v_lshl_add_u64 v[18:19], v[146:147], 0, s[52:53]
	v_lshl_add_u64 v[22:23], s[6:7], 0, v[18:19]
	v_cvt_f32_ubyte1_e32 v25, v204
	v_cvt_f32_ubyte0_e32 v24, v204
	v_cvt_f32_ubyte3_e32 v27, v204
	v_cvt_f32_ubyte2_e32 v26, v204
	v_cvt_f32_ubyte1_e32 v29, v205
	v_cvt_f32_ubyte0_e32 v28, v205
	v_cvt_f32_ubyte3_e32 v31, v205
	v_cvt_f32_ubyte2_e32 v30, v205
	v_pk_mul_f32 v[16:17], v[24:25], s[40:41] op_sel_hi:[1,0]
	v_pk_mul_f32 v[24:25], v[26:27], s[40:41] op_sel_hi:[1,0]
	v_pk_mul_f32 v[26:27], v[28:29], s[40:41] op_sel_hi:[1,0]
	v_pk_mul_f32 v[28:29], v[30:31], s[40:41] op_sel_hi:[1,0]
	v_pk_mul_f32 v[12:13], v[12:13], v[16:17]
	v_pk_mul_f32 v[14:15], v[14:15], v[24:25]
	v_pk_mul_f32 v[16:17], v[8:9], v[26:27]
	v_pk_mul_f32 v[24:25], v[10:11], v[28:29]
	v_cvt_pk_bf16_f32 v8, v12, v13
	v_cvt_pk_bf16_f32 v9, v14, v15
	v_cvt_pk_bf16_f32 v10, v16, v17
	v_cvt_pk_bf16_f32 v11, v24, v25
	global_store_dwordx4 v[20:21], v[8:11], off
	s_nop 0
	v_cvt_f32_ubyte1_e32 v13, v206
	v_lshl_add_u64 v[10:11], v[18:19], 1, s[12:13]
	v_cvt_f32_ubyte0_e32 v12, v206
	v_cvt_f32_ubyte3_e32 v15, v206
	v_cvt_f32_ubyte2_e32 v14, v206
	v_cvt_f32_ubyte1_e32 v17, v207
	v_cvt_f32_ubyte0_e32 v16, v207
	v_cvt_f32_ubyte3_e32 v19, v207
	v_cvt_f32_ubyte2_e32 v18, v207
	v_pk_mul_f32 v[8:9], v[12:13], s[40:41] op_sel_hi:[1,0]
	v_pk_mul_f32 v[12:13], v[14:15], s[40:41] op_sel_hi:[1,0]
	v_pk_mul_f32 v[14:15], v[16:17], s[40:41] op_sel_hi:[1,0]
	v_pk_mul_f32 v[16:17], v[18:19], s[40:41] op_sel_hi:[1,0]
	v_pk_mul_f32 v[4:5], v[4:5], v[8:9]
	v_pk_mul_f32 v[6:7], v[6:7], v[12:13]
	v_pk_mul_f32 v[8:9], v[0:1], v[14:15]
	v_pk_mul_f32 v[12:13], v[2:3], v[16:17]
	v_cvt_pk_bf16_f32 v0, v4, v5
	v_cvt_pk_bf16_f32 v1, v6, v7
	v_cvt_pk_bf16_f32 v2, v8, v9
	v_cvt_pk_bf16_f32 v3, v12, v13
	global_store_dwordx4 v[10:11], v[0:3], off
	s_cbranch_vccnz .LBB0_954
	s_andn2_b64 vcc, exec, s[4:5]
	s_cbranch_vccnz .LBB0_953
	s_barrier
	s_branch .LBB0_953

; DI void unpack8(u32x4 w, float* f) { f[0] = bflo(w.x); f[1] = bfhi(w.x); f[2] = bflo(w.y); f[3] = bfhi(w.y); f[4] = bflo(w.z); f[5] = bfhi(w.z); f[6] = bflo(w.w); f[7] = bfhi(w.w); }
; DI u32x4 pack8(const float* f) { u32x4 w; w.x = pk2(f[0], f[1]); w.y = pk2(f[2], f[3]); w.z = pk2(f[4], f[5]); w.w = pk2(f[6], f[7]); return w; }
;     DI void operator()(AccRef acc, const Unit& u, int wr, int wc, int fr, int fq) const {
;         const int col0 = u.pn * 256 + wc * 32 + 8 * fq;
;         const int row0 = u.pm * 256 + wr * 64 + fr;
; #pragma unroll
;         for (int ai = 0; ai < 2; ++ai)
; #pragma unroll
;             for (int m = 0; m < 4; ++m) {
; #pragma unroll
;                 for (int bj = 0; bj < 2; ++bj) {
;                     const size_t o = (size_t)(row0 + ai * 128 + m * 16) * 2048 + col0 + bj * 128;
;                     const pg8::f32x4 v0 = acc[ai][bj][m][0], v1 = acc[ai][bj][m][1];
;                     float g[8], r[8]; unpack8_u8(*(const u32x2*)(G + o), g);
;                     r[0] = g[0] * v0[0]; r[1] = g[1] * v0[1]; r[2] = g[2] * v0[2]; r[3] = g[3] * v0[3];
;                     r[4] = g[4] * v1[0]; r[5] = g[5] * v1[1]; r[6] = g[6] * v1[2]; r[7] = g[7] * v1[3];
;                     if (add) { float t[8]; unpack8(*(const u32x4*)(MIX + o), t);
; #pragma unroll
;                         for (int j = 0; j < 8; ++j) r[j] += t[j]; }
;                     *(u32x4*)(MIX + o) = pack8(r);
;                 }
;             }
;     }
.LBB0_985:
	v_lshl_add_u32 v150, s58, 8, v129
	v_lshl_or_b32 v148, s79, 8, v153
	v_ashrrev_i32_e32 v151, 31, v150
	v_ashrrev_i32_e32 v149, 31, v148
	v_lshlrev_b64 v[146:147], 11, v[150:151]
	v_lshl_add_u64 v[146:147], v[146:147], 0, v[148:149]
	v_mov_b32_e32 v184, v146
	v_lshlrev_b32_e32 v185, 1, v146
	v_lshl_add_u64 v[158:159], s[6:7], 0, v[146:147]
	s_nop 0
	v_lshl_add_u64 v[166:167], v[146:147], 1, s[12:13]
	s_nop 0
	v_or_b32_e32 v168, 0x80, v146
	v_mov_b32_e32 v169, v147
	v_lshl_add_u64 v[170:171], s[6:7], 0, v[168:169]
	s_andn2_b64 vcc, exec, s[2:3]
	s_mov_b64 s[2:3], -1
	s_add_u32 s98, s6, 0x0
	s_addc_u32 s99, s7, 0
	s_add_u32 s100, s12, 0x0
	s_addc_u32 s101, s13, 0
	global_load_dwordx2 v[186:187], v184, s[98:99]
	global_load_dwordx2 v[188:189], v184, s[98:99] offset:128
	global_load_dwordx4 v[198:201], v185, s[100:101]
	global_load_dwordx4 v[202:205], v185, s[100:101] offset:256
	s_add_u32 s98, s6, 0x8000
	s_addc_u32 s99, s7, 0
	s_add_u32 s100, s12, 0x10000
	s_addc_u32 s101, s13, 0
	global_load_dwordx2 v[190:191], v184, s[98:99]
	global_load_dwordx2 v[192:193], v184, s[98:99] offset:128
	global_load_dwordx4 v[206:209], v185, s[100:101]
	global_load_dwordx4 v[210:213], v185, s[100:101] offset:256
	s_add_u32 s98, s6, 0x10000
	s_addc_u32 s99, s7, 0
	s_add_u32 s100, s12, 0x20000
	s_addc_u32 s101, s13, 0
	global_load_dwordx2 v[194:195], v184, s[98:99]
	global_load_dwordx2 v[196:197], v184, s[98:99] offset:128
	global_load_dwordx4 v[214:217], v185, s[100:101]
	global_load_dwordx4 v[218:221], v185, s[100:101] offset:256
	s_waitcnt vmcnt(0)
	v_cvt_f32_ubyte1_e32 v173, v186
	v_cvt_f32_ubyte0_e32 v172, v186
	v_cvt_f32_ubyte3_e32 v177, v186
	v_cvt_f32_ubyte2_e32 v176, v186
	v_cvt_f32_ubyte1_e32 v179, v187
	v_cvt_f32_ubyte0_e32 v178, v187
	v_cvt_f32_ubyte3_e32 v183, v187
	v_cvt_f32_ubyte2_e32 v182, v187
	v_lshlrev_b32_e32 v174, 16, v198
	v_and_b32_e32 v175, 0xffff0000, v198
	v_lshlrev_b32_e32 v162, 16, v199
	v_and_b32_e32 v163, 0xffff0000, v199
	v_lshlrev_b32_e32 v180, 16, v200
	v_and_b32_e32 v181, 0xffff0000, v200
	v_lshlrev_b32_e32 v158, 16, v201
	v_and_b32_e32 v159, 0xffff0000, v201
	v_pk_mul_f32 v[164:165], v[172:173], s[20:21] op_sel_hi:[1,0]
	v_pk_mul_f32 v[172:173], v[176:177], s[20:21] op_sel_hi:[1,0]
	v_pk_mul_f32 v[176:177], v[178:179], s[20:21] op_sel_hi:[1,0]
	v_pk_mul_f32 v[178:179], v[182:183], s[20:21] op_sel_hi:[1,0]
	v_pk_fma_f32 v[124:125], v[124:125], v[164:165], v[174:175]
	v_pk_fma_f32 v[126:127], v[126:127], v[172:173], v[162:163]
	v_pk_fma_f32 v[162:163], v[120:121], v[176:177], v[180:181]
	v_pk_fma_f32 v[158:159], v[122:123], v[178:179], v[158:159]
	v_cvt_pk_bf16_f32 v120, v124, v125
	v_cvt_pk_bf16_f32 v121, v126, v127
	v_cvt_pk_bf16_f32 v122, v162, v163
	v_cvt_pk_bf16_f32 v123, v158, v159
	global_store_dwordx4 v[166:167], v[120:123], off
	s_nop 0
	v_lshl_add_u64 v[126:127], v[168:169], 1, s[12:13]
	s_nop 0
	v_or_b32_e32 v158, 16, v150
	v_ashrrev_i32_e32 v159, 31, v158
	v_lshlrev_b64 v[158:159], 11, v[158:159]
	v_lshl_add_u64 v[158:159], v[158:159], 0, v[148:149]
	v_lshl_add_u64 v[162:163], s[6:7], 0, v[158:159]
	v_cvt_f32_ubyte1_e32 v165, v188
	v_cvt_f32_ubyte0_e32 v164, v188
	v_cvt_f32_ubyte3_e32 v169, v188
	v_cvt_f32_ubyte2_e32 v168, v188
	v_cvt_f32_ubyte1_e32 v171, v189
	v_cvt_f32_ubyte0_e32 v170, v189
	v_cvt_f32_ubyte3_e32 v175, v189
	v_cvt_f32_ubyte2_e32 v174, v189
	v_lshlrev_b32_e32 v166, 16, v202
	v_and_b32_e32 v167, 0xffff0000, v202
	v_lshlrev_b32_e32 v120, 16, v203
	v_and_b32_e32 v121, 0xffff0000, v203
	v_lshlrev_b32_e32 v172, 16, v204
	v_and_b32_e32 v173, 0xffff0000, v204
	v_lshlrev_b32_e32 v122, 16, v205
	v_and_b32_e32 v123, 0xffff0000, v205
	v_pk_mul_f32 v[124:125], v[164:165], s[20:21] op_sel_hi:[1,0]
	v_pk_mul_f32 v[164:165], v[168:169], s[20:21] op_sel_hi:[1,0]
	v_pk_mul_f32 v[168:169], v[170:171], s[20:21] op_sel_hi:[1,0]
	v_pk_mul_f32 v[170:171], v[174:175], s[20:21] op_sel_hi:[1,0]
	v_pk_fma_f32 v[116:117], v[116:117], v[124:125], v[166:167]
	v_pk_fma_f32 v[118:119], v[118:119], v[164:165], v[120:121]
	v_pk_fma_f32 v[120:121], v[112:113], v[168:169], v[172:173]
	v_pk_fma_f32 v[122:123], v[114:115], v[170:171], v[122:123]
	v_cvt_pk_bf16_f32 v112, v116, v117
	v_cvt_pk_bf16_f32 v113, v118, v119
	v_cvt_pk_bf16_f32 v114, v120, v121
	v_cvt_pk_bf16_f32 v115, v122, v123
	global_store_dwordx4 v[126:127], v[112:115], off
	s_nop 0
	v_lshl_add_u64 v[118:119], v[158:159], 1, s[12:13]
	s_nop 0
	v_or_b32_e32 v158, 0x80, v158
	v_lshl_add_u64 v[120:121], s[6:7], 0, v[158:159]
	v_cvt_f32_ubyte1_e32 v123, v190
	v_cvt_f32_ubyte0_e32 v122, v190
	v_cvt_f32_ubyte3_e32 v127, v190
	v_cvt_f32_ubyte2_e32 v126, v190
	v_cvt_f32_ubyte1_e32 v163, v191
	v_cvt_f32_ubyte0_e32 v162, v191
	v_cvt_f32_ubyte3_e32 v167, v191
	v_cvt_f32_ubyte2_e32 v166, v191
	v_lshlrev_b32_e32 v124, 16, v206
	v_and_b32_e32 v125, 0xffff0000, v206
	v_lshlrev_b32_e32 v112, 16, v207
	v_and_b32_e32 v113, 0xffff0000, v207
	v_lshlrev_b32_e32 v164, 16, v208
	v_and_b32_e32 v165, 0xffff0000, v208
	v_lshlrev_b32_e32 v114, 16, v209
	v_and_b32_e32 v115, 0xffff0000, v209
	v_pk_mul_f32 v[116:117], v[122:123], s[20:21] op_sel_hi:[1,0]
	v_pk_mul_f32 v[122:123], v[126:127], s[20:21] op_sel_hi:[1,0]
	v_pk_mul_f32 v[126:127], v[162:163], s[20:21] op_sel_hi:[1,0]
	v_pk_mul_f32 v[162:163], v[166:167], s[20:21] op_sel_hi:[1,0]
	v_pk_fma_f32 v[108:109], v[108:109], v[116:117], v[124:125]
	v_pk_fma_f32 v[110:111], v[110:111], v[122:123], v[112:113]
	v_pk_fma_f32 v[112:113], v[104:105], v[126:127], v[164:165]
	v_pk_fma_f32 v[114:115], v[106:107], v[162:163], v[114:115]
	v_cvt_pk_bf16_f32 v104, v108, v109
	v_cvt_pk_bf16_f32 v105, v110, v111
	v_cvt_pk_bf16_f32 v106, v112, v113
; DI void unpack8(u32x4 w, float* f) { f[0] = bflo(w.x); f[1] = bfhi(w.x); f[2] = bflo(w.y); f[3] = bfhi(w.y); f[4] = bflo(w.z); f[5] = bfhi(w.z); f[6] = bflo(w.w); f[7] = bfhi(w.w); }
; DI u32x4 pack8(const float* f) { u32x4 w; w.x = pk2(f[0], f[1]); w.y = pk2(f[2], f[3]); w.z = pk2(f[4], f[5]); w.w = pk2(f[6], f[7]); return w; }
;     DI void operator()(AccRef acc, const Unit& u, int wr, int wc, int fr, int fq) const {
;         const int col0 = u.pn * 256 + wc * 32 + 8 * fq;
;         const int row0 = u.pm * 256 + wr * 64 + fr;
; #pragma unroll
;         for (int ai = 0; ai < 2; ++ai)
; #pragma unroll
;             for (int m = 0; m < 4; ++m) {
; #pragma unroll
;                 for (int bj = 0; bj < 2; ++bj) {
;                     const size_t o = (size_t)(row0 + ai * 128 + m * 16) * 2048 + col0 + bj * 128;
;                     const pg8::f32x4 v0 = acc[ai][bj][m][0], v1 = acc[ai][bj][m][1];
;                     float g[8], r[8]; unpack8_u8(*(const u32x2*)(G + o), g);
;                     r[0] = g[0] * v0[0]; r[1] = g[1] * v0[1]; r[2] = g[2] * v0[2]; r[3] = g[3] * v0[3];
;                     r[4] = g[4] * v1[0]; r[5] = g[5] * v1[1]; r[6] = g[6] * v1[2]; r[7] = g[7] * v1[3];
;                     if (add) { float t[8]; unpack8(*(const u32x4*)(MIX + o), t);
; #pragma unroll
;                         for (int j = 0; j < 8; ++j) r[j] += t[j]; }
;                     *(u32x4*)(MIX + o) = pack8(r);
;                 }
;             }
;     }
	v_cvt_pk_bf16_f32 v107, v114, v115
	global_store_dwordx4 v[118:119], v[104:107], off
	s_nop 0
	v_lshl_add_u64 v[110:111], v[158:159], 1, s[12:13]
	s_nop 0
	v_or_b32_e32 v112, 32, v150
	v_ashrrev_i32_e32 v113, 31, v112
	v_lshlrev_b64 v[112:113], 11, v[112:113]
	v_lshl_add_u64 v[112:113], v[112:113], 0, v[148:149]
	v_lshl_add_u64 v[114:115], s[6:7], 0, v[112:113]
	v_cvt_f32_ubyte1_e32 v117, v192
	v_cvt_f32_ubyte0_e32 v116, v192
	v_cvt_f32_ubyte3_e32 v121, v192
	v_cvt_f32_ubyte2_e32 v120, v192
	v_cvt_f32_ubyte1_e32 v123, v193
	v_cvt_f32_ubyte0_e32 v122, v193
	v_cvt_f32_ubyte3_e32 v127, v193
	v_cvt_f32_ubyte2_e32 v126, v193
	v_lshlrev_b32_e32 v118, 16, v210
	v_and_b32_e32 v119, 0xffff0000, v210
	v_lshlrev_b32_e32 v104, 16, v211
	v_and_b32_e32 v105, 0xffff0000, v211
	v_lshlrev_b32_e32 v124, 16, v212
	v_and_b32_e32 v125, 0xffff0000, v212
	v_lshlrev_b32_e32 v106, 16, v213
	v_and_b32_e32 v107, 0xffff0000, v213
	v_pk_mul_f32 v[108:109], v[116:117], s[20:21] op_sel_hi:[1,0]
	v_pk_mul_f32 v[116:117], v[120:121], s[20:21] op_sel_hi:[1,0]
	v_pk_mul_f32 v[120:121], v[122:123], s[20:21] op_sel_hi:[1,0]
	v_pk_mul_f32 v[122:123], v[126:127], s[20:21] op_sel_hi:[1,0]
	v_pk_fma_f32 v[100:101], v[100:101], v[108:109], v[118:119]
	v_pk_fma_f32 v[102:103], v[102:103], v[116:117], v[104:105]
	v_pk_fma_f32 v[104:105], v[96:97], v[120:121], v[124:125]
	v_pk_fma_f32 v[106:107], v[98:99], v[122:123], v[106:107]
	v_cvt_pk_bf16_f32 v96, v100, v101
	v_cvt_pk_bf16_f32 v97, v102, v103
	v_cvt_pk_bf16_f32 v98, v104, v105
	v_cvt_pk_bf16_f32 v99, v106, v107
	global_store_dwordx4 v[110:111], v[96:99], off
	s_nop 0
	v_lshl_add_u64 v[102:103], v[112:113], 1, s[12:13]
	s_nop 0
	v_or_b32_e32 v112, 0x80, v112
	v_lshl_add_u64 v[104:105], s[6:7], 0, v[112:113]
	v_cvt_f32_ubyte1_e32 v107, v194
	v_cvt_f32_ubyte0_e32 v106, v194
	v_cvt_f32_ubyte3_e32 v111, v194
	v_cvt_f32_ubyte2_e32 v110, v194
	v_cvt_f32_ubyte1_e32 v115, v195
	v_cvt_f32_ubyte0_e32 v114, v195
	v_cvt_f32_ubyte3_e32 v119, v195
	v_cvt_f32_ubyte2_e32 v118, v195
	v_lshlrev_b32_e32 v108, 16, v214
	v_and_b32_e32 v109, 0xffff0000, v214
	v_lshlrev_b32_e32 v96, 16, v215
	v_and_b32_e32 v97, 0xffff0000, v215
	v_lshlrev_b32_e32 v116, 16, v216
	v_and_b32_e32 v117, 0xffff0000, v216
	v_lshlrev_b32_e32 v98, 16, v217
	v_and_b32_e32 v99, 0xffff0000, v217
	v_pk_mul_f32 v[100:101], v[106:107], s[20:21] op_sel_hi:[1,0]
	v_pk_mul_f32 v[106:107], v[110:111], s[20:21] op_sel_hi:[1,0]
	v_pk_mul_f32 v[110:111], v[114:115], s[20:21] op_sel_hi:[1,0]
	v_pk_mul_f32 v[114:115], v[118:119], s[20:21] op_sel_hi:[1,0]
	v_pk_fma_f32 v[92:93], v[92:93], v[100:101], v[108:109]
	v_pk_fma_f32 v[94:95], v[94:95], v[106:107], v[96:97]
	v_pk_fma_f32 v[96:97], v[88:89], v[110:111], v[116:117]
	v_pk_fma_f32 v[98:99], v[90:91], v[114:115], v[98:99]
	v_cvt_pk_bf16_f32 v88, v92, v93
	v_cvt_pk_bf16_f32 v89, v94, v95
	v_cvt_pk_bf16_f32 v90, v96, v97
	v_cvt_pk_bf16_f32 v91, v98, v99
	global_store_dwordx4 v[102:103], v[88:91], off
	s_nop 0
	v_lshl_add_u64 v[94:95], v[112:113], 1, s[12:13]
	s_nop 0
	v_or_b32_e32 v96, 48, v150
	v_ashrrev_i32_e32 v97, 31, v96
	v_lshlrev_b64 v[96:97], 11, v[96:97]
	v_lshl_add_u64 v[96:97], v[96:97], 0, v[148:149]
	v_lshl_add_u64 v[98:99], s[6:7], 0, v[96:97]
	v_cvt_f32_ubyte1_e32 v101, v196
	v_cvt_f32_ubyte0_e32 v100, v196
	v_cvt_f32_ubyte3_e32 v105, v196
	v_cvt_f32_ubyte2_e32 v104, v196
	v_cvt_f32_ubyte1_e32 v107, v197
	v_cvt_f32_ubyte0_e32 v106, v197
	v_cvt_f32_ubyte3_e32 v111, v197
	v_cvt_f32_ubyte2_e32 v110, v197
	v_lshlrev_b32_e32 v102, 16, v218
	v_and_b32_e32 v103, 0xffff0000, v218
	v_lshlrev_b32_e32 v88, 16, v219
	v_and_b32_e32 v89, 0xffff0000, v219
	v_lshlrev_b32_e32 v108, 16, v220
	v_and_b32_e32 v109, 0xffff0000, v220
	v_lshlrev_b32_e32 v90, 16, v221
	v_and_b32_e32 v91, 0xffff0000, v221
	v_pk_mul_f32 v[92:93], v[100:101], s[20:21] op_sel_hi:[1,0]
	v_pk_mul_f32 v[100:101], v[104:105], s[20:21] op_sel_hi:[1,0]
	v_pk_mul_f32 v[104:105], v[106:107], s[20:21] op_sel_hi:[1,0]
	v_pk_mul_f32 v[106:107], v[110:111], s[20:21] op_sel_hi:[1,0]
	v_pk_fma_f32 v[84:85], v[84:85], v[92:93], v[102:103]
	v_pk_fma_f32 v[86:87], v[86:87], v[100:101], v[88:89]
	v_pk_fma_f32 v[88:89], v[80:81], v[104:105], v[108:109]
	v_pk_fma_f32 v[90:91], v[82:83], v[106:107], v[90:91]
	v_cvt_pk_bf16_f32 v80, v84, v85
	v_cvt_pk_bf16_f32 v81, v86, v87
	v_cvt_pk_bf16_f32 v82, v88, v89
	v_cvt_pk_bf16_f32 v83, v90, v91
	global_store_dwordx4 v[94:95], v[80:83], off
	s_nop 0
	v_lshl_add_u64 v[86:87], v[96:97], 1, s[12:13]
	s_nop 0
	v_or_b32_e32 v96, 0x80, v96
	v_lshl_add_u64 v[88:89], s[6:7], 0, v[96:97]
	s_add_u32 s98, s6, 0x18000
	s_addc_u32 s99, s7, 0
	s_add_u32 s100, s12, 0x30000
	s_addc_u32 s101, s13, 0
	global_load_dwordx2 v[186:187], v184, s[98:99]
	global_load_dwordx2 v[188:189], v184, s[98:99] offset:128
	global_load_dwordx4 v[198:201], v185, s[100:101]
	global_load_dwordx4 v[202:205], v185, s[100:101] offset:256
	s_add_u32 s98, s6, 0x40000
	s_addc_u32 s99, s7, 0
	s_add_u32 s100, s12, 0x80000
	s_addc_u32 s101, s13, 0
	global_load_dwordx2 v[190:191], v184, s[98:99]
	global_load_dwordx2 v[192:193], v184, s[98:99] offset:128
	global_load_dwordx4 v[206:209], v185, s[100:101]
	global_load_dwordx4 v[210:213], v185, s[100:101] offset:256
	s_add_u32 s98, s6, 0x48000
	s_addc_u32 s99, s7, 0
	s_add_u32 s100, s12, 0x90000
	s_addc_u32 s101, s13, 0
	global_load_dwordx2 v[194:195], v184, s[98:99]
	global_load_dwordx2 v[196:197], v184, s[98:99] offset:128
	global_load_dwordx4 v[214:217], v185, s[100:101]
	global_load_dwordx4 v[218:221], v185, s[100:101] offset:256
	s_waitcnt vmcnt(0)
; DI void unpack8(u32x4 w, float* f) { f[0] = bflo(w.x); f[1] = bfhi(w.x); f[2] = bflo(w.y); f[3] = bfhi(w.y); f[4] = bflo(w.z); f[5] = bfhi(w.z); f[6] = bflo(w.w); f[7] = bfhi(w.w); }
; DI u32x4 pack8(const float* f) { u32x4 w; w.x = pk2(f[0], f[1]); w.y = pk2(f[2], f[3]); w.z = pk2(f[4], f[5]); w.w = pk2(f[6], f[7]); return w; }
;     DI void operator()(AccRef acc, const Unit& u, int wr, int wc, int fr, int fq) const {
;         const int col0 = u.pn * 256 + wc * 32 + 8 * fq;
;         const int row0 = u.pm * 256 + wr * 64 + fr;
; #pragma unroll
;         for (int ai = 0; ai < 2; ++ai)
; #pragma unroll
;             for (int m = 0; m < 4; ++m) {
; #pragma unroll
;                 for (int bj = 0; bj < 2; ++bj) {
;                     const size_t o = (size_t)(row0 + ai * 128 + m * 16) * 2048 + col0 + bj * 128;
;                     const pg8::f32x4 v0 = acc[ai][bj][m][0], v1 = acc[ai][bj][m][1];
;                     float g[8], r[8]; unpack8_u8(*(const u32x2*)(G + o), g);
;                     r[0] = g[0] * v0[0]; r[1] = g[1] * v0[1]; r[2] = g[2] * v0[2]; r[3] = g[3] * v0[3];
;                     r[4] = g[4] * v1[0]; r[5] = g[5] * v1[1]; r[6] = g[6] * v1[2]; r[7] = g[7] * v1[3];
;                     if (add) { float t[8]; unpack8(*(const u32x4*)(MIX + o), t);
; #pragma unroll
;                         for (int j = 0; j < 8; ++j) r[j] += t[j]; }
;                     *(u32x4*)(MIX + o) = pack8(r);
;                 }
;             }
;     }
	v_cvt_f32_ubyte1_e32 v91, v186
	v_cvt_f32_ubyte0_e32 v90, v186
	v_cvt_f32_ubyte3_e32 v95, v186
	v_cvt_f32_ubyte2_e32 v94, v186
	v_cvt_f32_ubyte1_e32 v99, v187
	v_cvt_f32_ubyte0_e32 v98, v187
	v_cvt_f32_ubyte3_e32 v103, v187
	v_cvt_f32_ubyte2_e32 v102, v187
	v_lshlrev_b32_e32 v92, 16, v198
	v_and_b32_e32 v93, 0xffff0000, v198
	v_lshlrev_b32_e32 v80, 16, v199
	v_and_b32_e32 v81, 0xffff0000, v199
	v_lshlrev_b32_e32 v100, 16, v200
	v_and_b32_e32 v101, 0xffff0000, v200
	v_lshlrev_b32_e32 v82, 16, v201
	v_and_b32_e32 v83, 0xffff0000, v201
	v_pk_mul_f32 v[84:85], v[90:91], s[20:21] op_sel_hi:[1,0]
	v_pk_mul_f32 v[90:91], v[94:95], s[20:21] op_sel_hi:[1,0]
	v_pk_mul_f32 v[94:95], v[98:99], s[20:21] op_sel_hi:[1,0]
	v_pk_mul_f32 v[98:99], v[102:103], s[20:21] op_sel_hi:[1,0]
	v_pk_fma_f32 v[76:77], v[76:77], v[84:85], v[92:93]
	v_pk_fma_f32 v[78:79], v[78:79], v[90:91], v[80:81]
	v_pk_fma_f32 v[80:81], v[72:73], v[94:95], v[100:101]
	v_pk_fma_f32 v[82:83], v[74:75], v[98:99], v[82:83]
	v_cvt_pk_bf16_f32 v72, v76, v77
	v_cvt_pk_bf16_f32 v73, v78, v79
	v_cvt_pk_bf16_f32 v74, v80, v81
	v_cvt_pk_bf16_f32 v75, v82, v83
	global_store_dwordx4 v[86:87], v[72:75], off
	s_nop 0
	v_lshl_add_u64 v[78:79], v[96:97], 1, s[12:13]
	s_nop 0
	v_lshl_add_u64 v[80:81], v[146:147], 0, s[0:1]
	v_lshl_add_u64 v[82:83], s[6:7], 0, v[80:81]
	v_cvt_f32_ubyte1_e32 v85, v188
	v_cvt_f32_ubyte0_e32 v84, v188
	v_cvt_f32_ubyte3_e32 v89, v188
	v_cvt_f32_ubyte2_e32 v88, v188
	v_cvt_f32_ubyte1_e32 v91, v189
	v_cvt_f32_ubyte0_e32 v90, v189
	v_cvt_f32_ubyte3_e32 v95, v189
	v_cvt_f32_ubyte2_e32 v94, v189
	v_lshlrev_b32_e32 v86, 16, v202
	v_and_b32_e32 v87, 0xffff0000, v202
	v_lshlrev_b32_e32 v72, 16, v203
	v_and_b32_e32 v73, 0xffff0000, v203
	v_lshlrev_b32_e32 v92, 16, v204
	v_and_b32_e32 v93, 0xffff0000, v204
	v_lshlrev_b32_e32 v74, 16, v205
	v_and_b32_e32 v75, 0xffff0000, v205
	v_pk_mul_f32 v[76:77], v[84:85], s[20:21] op_sel_hi:[1,0]
	v_pk_mul_f32 v[84:85], v[88:89], s[20:21] op_sel_hi:[1,0]
	v_pk_mul_f32 v[88:89], v[90:91], s[20:21] op_sel_hi:[1,0]
	v_pk_mul_f32 v[90:91], v[94:95], s[20:21] op_sel_hi:[1,0]
	v_pk_fma_f32 v[68:69], v[68:69], v[76:77], v[86:87]
	v_pk_fma_f32 v[70:71], v[70:71], v[84:85], v[72:73]
	v_pk_fma_f32 v[72:73], v[64:65], v[88:89], v[92:93]
	v_pk_fma_f32 v[74:75], v[66:67], v[90:91], v[74:75]
	v_cvt_pk_bf16_f32 v64, v68, v69
	v_cvt_pk_bf16_f32 v65, v70, v71
	v_cvt_pk_bf16_f32 v66, v72, v73
	v_cvt_pk_bf16_f32 v67, v74, v75
	global_store_dwordx4 v[78:79], v[64:67], off
	s_nop 0
	v_lshl_add_u64 v[70:71], v[80:81], 1, s[12:13]
	s_nop 0
	v_lshl_add_u64 v[72:73], v[146:147], 0, s[16:17]
	v_lshl_add_u64 v[74:75], s[6:7], 0, v[72:73]
	v_cvt_f32_ubyte1_e32 v77, v190
	v_cvt_f32_ubyte0_e32 v76, v190
	v_cvt_f32_ubyte3_e32 v81, v190
	v_cvt_f32_ubyte2_e32 v80, v190
	v_cvt_f32_ubyte1_e32 v83, v191
	v_cvt_f32_ubyte0_e32 v82, v191
	v_cvt_f32_ubyte3_e32 v87, v191
	v_cvt_f32_ubyte2_e32 v86, v191
	v_lshlrev_b32_e32 v78, 16, v206
	v_and_b32_e32 v79, 0xffff0000, v206
	v_lshlrev_b32_e32 v64, 16, v207
	v_and_b32_e32 v65, 0xffff0000, v207
	v_lshlrev_b32_e32 v84, 16, v208
	v_and_b32_e32 v85, 0xffff0000, v208
	v_lshlrev_b32_e32 v66, 16, v209
	v_and_b32_e32 v67, 0xffff0000, v209
	v_pk_mul_f32 v[68:69], v[76:77], s[20:21] op_sel_hi:[1,0]
	v_pk_mul_f32 v[76:77], v[80:81], s[20:21] op_sel_hi:[1,0]
	v_pk_mul_f32 v[80:81], v[82:83], s[20:21] op_sel_hi:[1,0]
	v_pk_mul_f32 v[82:83], v[86:87], s[20:21] op_sel_hi:[1,0]
	v_pk_fma_f32 v[60:61], v[60:61], v[68:69], v[78:79]
	v_pk_fma_f32 v[62:63], v[62:63], v[76:77], v[64:65]
	v_pk_fma_f32 v[64:65], v[56:57], v[80:81], v[84:85]
	v_pk_fma_f32 v[66:67], v[58:59], v[82:83], v[66:67]
	v_cvt_pk_bf16_f32 v56, v60, v61
	v_cvt_pk_bf16_f32 v57, v62, v63
	v_cvt_pk_bf16_f32 v58, v64, v65
	v_cvt_pk_bf16_f32 v59, v66, v67
	global_store_dwordx4 v[70:71], v[56:59], off
	s_nop 0
	v_lshl_add_u64 v[62:63], v[72:73], 1, s[12:13]
	s_nop 0
	v_lshl_add_u64 v[64:65], v[146:147], 0, s[22:23]
	v_lshl_add_u64 v[66:67], s[6:7], 0, v[64:65]
	v_cvt_f32_ubyte1_e32 v69, v192
	v_cvt_f32_ubyte0_e32 v68, v192
	v_cvt_f32_ubyte3_e32 v73, v192
	v_cvt_f32_ubyte2_e32 v72, v192
	v_cvt_f32_ubyte1_e32 v75, v193
	v_cvt_f32_ubyte0_e32 v74, v193
	v_cvt_f32_ubyte3_e32 v79, v193
	v_cvt_f32_ubyte2_e32 v78, v193
	v_lshlrev_b32_e32 v70, 16, v210
	v_and_b32_e32 v71, 0xffff0000, v210
	v_lshlrev_b32_e32 v56, 16, v211
	v_and_b32_e32 v57, 0xffff0000, v211
	v_lshlrev_b32_e32 v76, 16, v212
	v_and_b32_e32 v77, 0xffff0000, v212
	v_lshlrev_b32_e32 v58, 16, v213
	v_and_b32_e32 v59, 0xffff0000, v213
	v_pk_mul_f32 v[60:61], v[68:69], s[20:21] op_sel_hi:[1,0]
	v_pk_mul_f32 v[68:69], v[72:73], s[20:21] op_sel_hi:[1,0]
	v_pk_mul_f32 v[72:73], v[74:75], s[20:21] op_sel_hi:[1,0]
	v_pk_mul_f32 v[74:75], v[78:79], s[20:21] op_sel_hi:[1,0]
	v_pk_fma_f32 v[52:53], v[52:53], v[60:61], v[70:71]
	v_pk_fma_f32 v[54:55], v[54:55], v[68:69], v[56:57]
	v_pk_fma_f32 v[56:57], v[48:49], v[72:73], v[76:77]
	v_pk_fma_f32 v[58:59], v[50:51], v[74:75], v[58:59]
	v_cvt_pk_bf16_f32 v48, v52, v53
	v_cvt_pk_bf16_f32 v49, v54, v55
	v_cvt_pk_bf16_f32 v50, v56, v57
	v_cvt_pk_bf16_f32 v51, v58, v59
	global_store_dwordx4 v[62:63], v[48:51], off
	s_nop 0
	v_lshl_add_u64 v[54:55], v[64:65], 1, s[12:13]
	s_nop 0
	v_lshl_add_u64 v[56:57], v[146:147], 0, s[40:41]
	v_lshl_add_u64 v[58:59], s[6:7], 0, v[56:57]
	v_cvt_f32_ubyte1_e32 v61, v194
	v_cvt_f32_ubyte0_e32 v60, v194
	v_cvt_f32_ubyte3_e32 v65, v194
	v_cvt_f32_ubyte2_e32 v64, v194
	v_cvt_f32_ubyte1_e32 v67, v195
	v_cvt_f32_ubyte0_e32 v66, v195
	v_cvt_f32_ubyte3_e32 v71, v195
	v_cvt_f32_ubyte2_e32 v70, v195
	v_lshlrev_b32_e32 v62, 16, v214
	v_and_b32_e32 v63, 0xffff0000, v214
; DI void unpack8(u32x4 w, float* f) { f[0] = bflo(w.x); f[1] = bfhi(w.x); f[2] = bflo(w.y); f[3] = bfhi(w.y); f[4] = bflo(w.z); f[5] = bfhi(w.z); f[6] = bflo(w.w); f[7] = bfhi(w.w); }
; DI u32x4 pack8(const float* f) { u32x4 w; w.x = pk2(f[0], f[1]); w.y = pk2(f[2], f[3]); w.z = pk2(f[4], f[5]); w.w = pk2(f[6], f[7]); return w; }
;     DI void operator()(AccRef acc, const Unit& u, int wr, int wc, int fr, int fq) const {
;         const int col0 = u.pn * 256 + wc * 32 + 8 * fq;
;         const int row0 = u.pm * 256 + wr * 64 + fr;
; #pragma unroll
;         for (int ai = 0; ai < 2; ++ai)
; #pragma unroll
;             for (int m = 0; m < 4; ++m) {
; #pragma unroll
;                 for (int bj = 0; bj < 2; ++bj) {
;                     const size_t o = (size_t)(row0 + ai * 128 + m * 16) * 2048 + col0 + bj * 128;
;                     const pg8::f32x4 v0 = acc[ai][bj][m][0], v1 = acc[ai][bj][m][1];
;                     float g[8], r[8]; unpack8_u8(*(const u32x2*)(G + o), g);
;                     r[0] = g[0] * v0[0]; r[1] = g[1] * v0[1]; r[2] = g[2] * v0[2]; r[3] = g[3] * v0[3];
;                     r[4] = g[4] * v1[0]; r[5] = g[5] * v1[1]; r[6] = g[6] * v1[2]; r[7] = g[7] * v1[3];
;                     if (add) { float t[8]; unpack8(*(const u32x4*)(MIX + o), t);
; #pragma unroll
;                         for (int j = 0; j < 8; ++j) r[j] += t[j]; }
;                     *(u32x4*)(MIX + o) = pack8(r);
;                 }
;             }
;     }
	v_lshlrev_b32_e32 v48, 16, v215
	v_and_b32_e32 v49, 0xffff0000, v215
	v_lshlrev_b32_e32 v68, 16, v216
	v_and_b32_e32 v69, 0xffff0000, v216
	v_lshlrev_b32_e32 v50, 16, v217
	v_and_b32_e32 v51, 0xffff0000, v217
	v_pk_mul_f32 v[52:53], v[60:61], s[20:21] op_sel_hi:[1,0]
	v_pk_mul_f32 v[60:61], v[64:65], s[20:21] op_sel_hi:[1,0]
	v_pk_mul_f32 v[64:65], v[66:67], s[20:21] op_sel_hi:[1,0]
	v_pk_mul_f32 v[66:67], v[70:71], s[20:21] op_sel_hi:[1,0]
	v_pk_fma_f32 v[44:45], v[44:45], v[52:53], v[62:63]
	v_pk_fma_f32 v[46:47], v[46:47], v[60:61], v[48:49]
	v_pk_fma_f32 v[48:49], v[40:41], v[64:65], v[68:69]
	v_pk_fma_f32 v[50:51], v[42:43], v[66:67], v[50:51]
	v_cvt_pk_bf16_f32 v40, v44, v45
	v_cvt_pk_bf16_f32 v41, v46, v47
	v_cvt_pk_bf16_f32 v42, v48, v49
	v_cvt_pk_bf16_f32 v43, v50, v51
	global_store_dwordx4 v[54:55], v[40:43], off
	s_nop 0
	v_lshl_add_u64 v[46:47], v[56:57], 1, s[12:13]
	s_nop 0
	v_lshl_add_u64 v[48:49], v[146:147], 0, s[42:43]
	v_lshl_add_u64 v[50:51], s[6:7], 0, v[48:49]
	v_cvt_f32_ubyte1_e32 v53, v196
	v_cvt_f32_ubyte0_e32 v52, v196
	v_cvt_f32_ubyte3_e32 v57, v196
	v_cvt_f32_ubyte2_e32 v56, v196
	v_cvt_f32_ubyte1_e32 v59, v197
	v_cvt_f32_ubyte0_e32 v58, v197
	v_cvt_f32_ubyte3_e32 v63, v197
	v_cvt_f32_ubyte2_e32 v62, v197
	v_lshlrev_b32_e32 v54, 16, v218
	v_and_b32_e32 v55, 0xffff0000, v218
	v_lshlrev_b32_e32 v40, 16, v219
	v_and_b32_e32 v41, 0xffff0000, v219
	v_lshlrev_b32_e32 v60, 16, v220
	v_and_b32_e32 v61, 0xffff0000, v220
	v_lshlrev_b32_e32 v42, 16, v221
	v_and_b32_e32 v43, 0xffff0000, v221
	v_pk_mul_f32 v[44:45], v[52:53], s[20:21] op_sel_hi:[1,0]
	v_pk_mul_f32 v[52:53], v[56:57], s[20:21] op_sel_hi:[1,0]
	v_pk_mul_f32 v[56:57], v[58:59], s[20:21] op_sel_hi:[1,0]
	v_pk_mul_f32 v[58:59], v[62:63], s[20:21] op_sel_hi:[1,0]
	v_pk_fma_f32 v[36:37], v[36:37], v[44:45], v[54:55]
	v_pk_fma_f32 v[38:39], v[38:39], v[52:53], v[40:41]
	v_pk_fma_f32 v[40:41], v[32:33], v[56:57], v[60:61]
	v_pk_fma_f32 v[42:43], v[34:35], v[58:59], v[42:43]
	v_cvt_pk_bf16_f32 v32, v36, v37
	v_cvt_pk_bf16_f32 v33, v38, v39
	v_cvt_pk_bf16_f32 v34, v40, v41
	v_cvt_pk_bf16_f32 v35, v42, v43
	global_store_dwordx4 v[46:47], v[32:35], off
	s_nop 0
	v_lshl_add_u64 v[38:39], v[48:49], 1, s[12:13]
	s_nop 0
	v_lshl_add_u64 v[40:41], v[146:147], 0, s[44:45]
	v_lshl_add_u64 v[42:43], s[6:7], 0, v[40:41]
	s_add_u32 s98, s6, 0x50000
	s_addc_u32 s99, s7, 0
	s_add_u32 s100, s12, 0xa0000
	s_addc_u32 s101, s13, 0
	global_load_dwordx2 v[186:187], v184, s[98:99]
	global_load_dwordx2 v[188:189], v184, s[98:99] offset:128
	global_load_dwordx4 v[198:201], v185, s[100:101]
	global_load_dwordx4 v[202:205], v185, s[100:101] offset:256
	s_add_u32 s98, s6, 0x58000
	s_addc_u32 s99, s7, 0
	s_add_u32 s100, s12, 0xb0000
	s_addc_u32 s101, s13, 0
	global_load_dwordx2 v[190:191], v184, s[98:99]
	global_load_dwordx2 v[192:193], v184, s[98:99] offset:128
	global_load_dwordx4 v[206:209], v185, s[100:101]
	global_load_dwordx4 v[210:213], v185, s[100:101] offset:256
	s_waitcnt vmcnt(0)
; DI void unpack8(u32x4 w, float* f) { f[0] = bflo(w.x); f[1] = bfhi(w.x); f[2] = bflo(w.y); f[3] = bfhi(w.y); f[4] = bflo(w.z); f[5] = bfhi(w.z); f[6] = bflo(w.w); f[7] = bfhi(w.w); }
; DI u32x4 pack8(const float* f) { u32x4 w; w.x = pk2(f[0], f[1]); w.y = pk2(f[2], f[3]); w.z = pk2(f[4], f[5]); w.w = pk2(f[6], f[7]); return w; }
;     DI void operator()(AccRef acc, const Unit& u, int wr, int wc, int fr, int fq) const {
;         const int col0 = u.pn * 256 + wc * 32 + 8 * fq;
;         const int row0 = u.pm * 256 + wr * 64 + fr;
; #pragma unroll
;         for (int ai = 0; ai < 2; ++ai)
; #pragma unroll
;             for (int m = 0; m < 4; ++m) {
; #pragma unroll
;                 for (int bj = 0; bj < 2; ++bj) {
;                     const size_t o = (size_t)(row0 + ai * 128 + m * 16) * 2048 + col0 + bj * 128;
;                     const pg8::f32x4 v0 = acc[ai][bj][m][0], v1 = acc[ai][bj][m][1];
;                     float g[8], r[8]; unpack8_u8(*(const u32x2*)(G + o), g);
;                     r[0] = g[0] * v0[0]; r[1] = g[1] * v0[1]; r[2] = g[2] * v0[2]; r[3] = g[3] * v0[3];
;                     r[4] = g[4] * v1[0]; r[5] = g[5] * v1[1]; r[6] = g[6] * v1[2]; r[7] = g[7] * v1[3];
;                     if (add) { float t[8]; unpack8(*(const u32x4*)(MIX + o), t);
; #pragma unroll
;                         for (int j = 0; j < 8; ++j) r[j] += t[j]; }
;                     *(u32x4*)(MIX + o) = pack8(r);
;                 }
;             }
;     }
	v_cvt_f32_ubyte1_e32 v45, v186
	v_cvt_f32_ubyte0_e32 v44, v186
	v_cvt_f32_ubyte3_e32 v49, v186
	v_cvt_f32_ubyte2_e32 v48, v186
	v_cvt_f32_ubyte1_e32 v51, v187
	v_cvt_f32_ubyte0_e32 v50, v187
	v_cvt_f32_ubyte3_e32 v55, v187
	v_cvt_f32_ubyte2_e32 v54, v187
	v_lshlrev_b32_e32 v46, 16, v198
	v_and_b32_e32 v47, 0xffff0000, v198
	v_lshlrev_b32_e32 v32, 16, v199
	v_and_b32_e32 v33, 0xffff0000, v199
	v_lshlrev_b32_e32 v52, 16, v200
	v_and_b32_e32 v53, 0xffff0000, v200
	v_lshlrev_b32_e32 v34, 16, v201
	v_and_b32_e32 v35, 0xffff0000, v201
	v_pk_mul_f32 v[36:37], v[44:45], s[20:21] op_sel_hi:[1,0]
	v_pk_mul_f32 v[44:45], v[48:49], s[20:21] op_sel_hi:[1,0]
	v_pk_mul_f32 v[48:49], v[50:51], s[20:21] op_sel_hi:[1,0]
	v_pk_mul_f32 v[50:51], v[54:55], s[20:21] op_sel_hi:[1,0]
	v_pk_fma_f32 v[28:29], v[28:29], v[36:37], v[46:47]
	v_pk_fma_f32 v[30:31], v[30:31], v[44:45], v[32:33]
	v_pk_fma_f32 v[32:33], v[24:25], v[48:49], v[52:53]
	v_pk_fma_f32 v[34:35], v[26:27], v[50:51], v[34:35]
	v_cvt_pk_bf16_f32 v24, v28, v29
	v_cvt_pk_bf16_f32 v25, v30, v31
	v_cvt_pk_bf16_f32 v26, v32, v33
	v_cvt_pk_bf16_f32 v27, v34, v35
	global_store_dwordx4 v[38:39], v[24:27], off
	s_nop 0
	v_lshl_add_u64 v[30:31], v[40:41], 1, s[12:13]
	s_nop 0
	v_lshl_add_u64 v[32:33], v[146:147], 0, s[46:47]
	v_lshl_add_u64 v[34:35], s[6:7], 0, v[32:33]
	v_cvt_f32_ubyte1_e32 v37, v188
	v_cvt_f32_ubyte0_e32 v36, v188
	v_cvt_f32_ubyte3_e32 v41, v188
	v_cvt_f32_ubyte2_e32 v40, v188
	v_cvt_f32_ubyte1_e32 v43, v189
	v_cvt_f32_ubyte0_e32 v42, v189
	v_cvt_f32_ubyte3_e32 v47, v189
	v_cvt_f32_ubyte2_e32 v46, v189
	v_lshlrev_b32_e32 v38, 16, v202
	v_and_b32_e32 v39, 0xffff0000, v202
	v_lshlrev_b32_e32 v24, 16, v203
	v_and_b32_e32 v25, 0xffff0000, v203
	v_lshlrev_b32_e32 v44, 16, v204
	v_and_b32_e32 v45, 0xffff0000, v204
	v_lshlrev_b32_e32 v26, 16, v205
	v_and_b32_e32 v27, 0xffff0000, v205
	v_pk_mul_f32 v[28:29], v[36:37], s[20:21] op_sel_hi:[1,0]
	v_pk_mul_f32 v[36:37], v[40:41], s[20:21] op_sel_hi:[1,0]
	v_pk_mul_f32 v[40:41], v[42:43], s[20:21] op_sel_hi:[1,0]
	v_pk_mul_f32 v[42:43], v[46:47], s[20:21] op_sel_hi:[1,0]
	v_pk_fma_f32 v[20:21], v[20:21], v[28:29], v[38:39]
	v_pk_fma_f32 v[22:23], v[22:23], v[36:37], v[24:25]
	v_pk_fma_f32 v[24:25], v[16:17], v[40:41], v[44:45]
	v_pk_fma_f32 v[26:27], v[18:19], v[42:43], v[26:27]
	v_cvt_pk_bf16_f32 v16, v20, v21
	v_cvt_pk_bf16_f32 v17, v22, v23
	v_cvt_pk_bf16_f32 v18, v24, v25
	v_cvt_pk_bf16_f32 v19, v26, v27
	global_store_dwordx4 v[30:31], v[16:19], off
	s_nop 0
	v_lshl_add_u64 v[22:23], v[32:33], 1, s[12:13]
	s_nop 0
	v_lshl_add_u64 v[24:25], v[146:147], 0, s[48:49]
	v_lshl_add_u64 v[26:27], s[6:7], 0, v[24:25]
	v_cvt_f32_ubyte1_e32 v29, v190
	v_cvt_f32_ubyte0_e32 v28, v190
	v_cvt_f32_ubyte3_e32 v33, v190
	v_cvt_f32_ubyte2_e32 v32, v190
	v_cvt_f32_ubyte1_e32 v35, v191
	v_cvt_f32_ubyte0_e32 v34, v191
	v_cvt_f32_ubyte3_e32 v39, v191
	v_cvt_f32_ubyte2_e32 v38, v191
	v_lshlrev_b32_e32 v30, 16, v206
	v_and_b32_e32 v31, 0xffff0000, v206
	v_lshlrev_b32_e32 v16, 16, v207
	v_and_b32_e32 v17, 0xffff0000, v207
	v_lshlrev_b32_e32 v36, 16, v208
	v_and_b32_e32 v37, 0xffff0000, v208
	v_lshlrev_b32_e32 v18, 16, v209
	v_and_b32_e32 v19, 0xffff0000, v209
	v_pk_mul_f32 v[20:21], v[28:29], s[20:21] op_sel_hi:[1,0]
	v_pk_mul_f32 v[28:29], v[32:33], s[20:21] op_sel_hi:[1,0]
	v_pk_mul_f32 v[32:33], v[34:35], s[20:21] op_sel_hi:[1,0]
	v_pk_mul_f32 v[34:35], v[38:39], s[20:21] op_sel_hi:[1,0]
	v_pk_fma_f32 v[12:13], v[12:13], v[20:21], v[30:31]
	v_pk_fma_f32 v[14:15], v[14:15], v[28:29], v[16:17]
	v_pk_fma_f32 v[16:17], v[8:9], v[32:33], v[36:37]
	v_pk_fma_f32 v[18:19], v[10:11], v[34:35], v[18:19]
	v_cvt_pk_bf16_f32 v8, v12, v13
	v_cvt_pk_bf16_f32 v9, v14, v15
	v_cvt_pk_bf16_f32 v10, v16, v17
	v_cvt_pk_bf16_f32 v11, v18, v19
	global_store_dwordx4 v[22:23], v[8:11], off
	s_nop 0
	v_lshl_add_u64 v[14:15], v[24:25], 1, s[12:13]
	s_nop 0
	v_cvt_f32_ubyte1_e32 v17, v192
	v_cvt_f32_ubyte0_e32 v16, v192
	v_cvt_f32_ubyte3_e32 v21, v192
	v_cvt_f32_ubyte2_e32 v20, v192
	v_cvt_f32_ubyte1_e32 v23, v193
	v_cvt_f32_ubyte0_e32 v22, v193
	v_cvt_f32_ubyte3_e32 v27, v193
	v_cvt_f32_ubyte2_e32 v26, v193
	v_lshlrev_b32_e32 v18, 16, v210
	v_and_b32_e32 v19, 0xffff0000, v210
	v_lshlrev_b32_e32 v8, 16, v211
	v_and_b32_e32 v9, 0xffff0000, v211
	v_lshlrev_b32_e32 v24, 16, v212
	v_and_b32_e32 v25, 0xffff0000, v212
	v_lshlrev_b32_e32 v10, 16, v213
	v_and_b32_e32 v11, 0xffff0000, v213
	v_pk_mul_f32 v[12:13], v[16:17], s[20:21] op_sel_hi:[1,0]
	v_pk_mul_f32 v[16:17], v[20:21], s[20:21] op_sel_hi:[1,0]
	v_pk_mul_f32 v[20:21], v[22:23], s[20:21] op_sel_hi:[1,0]
	v_pk_mul_f32 v[22:23], v[26:27], s[20:21] op_sel_hi:[1,0]
	v_pk_fma_f32 v[4:5], v[4:5], v[12:13], v[18:19]
	v_pk_fma_f32 v[6:7], v[6:7], v[16:17], v[8:9]
	v_pk_fma_f32 v[8:9], v[0:1], v[20:21], v[24:25]
	v_pk_fma_f32 v[10:11], v[2:3], v[22:23], v[10:11]
	v_cvt_pk_bf16_f32 v0, v4, v5
	v_cvt_pk_bf16_f32 v1, v6, v7
	v_cvt_pk_bf16_f32 v2, v8, v9
	v_cvt_pk_bf16_f32 v3, v10, v11
	global_store_dwordx4 v[14:15], v[0:3], off
	s_cbranch_vccnz .LBB0_978
	s_andn2_b64 vcc, exec, s[4:5]
	s_cbranch_vccnz .LBB0_977
	s_barrier
	s_branch .LBB0_977

; #define LAS __attribute__((address_space(3)))
; __global__ void __launch_bounds__(512, 2) mega_fwd(Args a) {
;     extern __shared__ __attribute__((aligned(16))) unsigned char lds_raw[];
;     LAS unsigned char* lds = (LAS unsigned char*)lds_raw;
;     cg::grid_group grid = cg::this_grid();
;     const int tid = threadIdx.x, lane = tid & 63, wave = __builtin_amdgcn_readfirstlane(tid >> 6);
	.amdhsa_kernel _Z8mega_fwd4Args
		.amdhsa_group_segment_fixed_size 0
		.amdhsa_private_segment_fixed_size 0
		.amdhsa_kernarg_size 472
		.amdhsa_user_sgpr_count 2
		.amdhsa_user_sgpr_dispatch_ptr 0
		.amdhsa_user_sgpr_queue_ptr 0
		.amdhsa_user_sgpr_kernarg_segment_ptr 1
		.amdhsa_user_sgpr_dispatch_id 0
		.amdhsa_user_sgpr_kernarg_preload_length 0
		.amdhsa_user_sgpr_kernarg_preload_offset 0
		.amdhsa_user_sgpr_private_segment_size 0
		.amdhsa_uses_dynamic_stack 0
		.amdhsa_enable_private_segment 0
		.amdhsa_system_sgpr_workgroup_id_x 1
		.amdhsa_system_sgpr_workgroup_id_y 0
		.amdhsa_system_sgpr_workgroup_id_z 0
		.amdhsa_system_sgpr_workgroup_info 0
		.amdhsa_system_vgpr_workitem_id 2
		.amdhsa_next_free_vgpr 255
		.amdhsa_next_free_sgpr 102
		.amdhsa_accum_offset 256
		.amdhsa_reserve_vcc 1
		.amdhsa_float_round_mode_32 0
		.amdhsa_float_round_mode_16_64 0
		.amdhsa_float_denorm_mode_32 3
		.amdhsa_float_denorm_mode_16_64 3
		.amdhsa_dx10_clamp 1
		.amdhsa_ieee_mode 1
		.amdhsa_fp16_overflow 0
		.amdhsa_tg_split 0
		.amdhsa_exception_fp_ieee_invalid_op 0
		.amdhsa_exception_fp_denorm_src 0
		.amdhsa_exception_fp_ieee_div_zero 0
		.amdhsa_exception_fp_ieee_overflow 0
		.amdhsa_exception_fp_ieee_underflow 0
		.amdhsa_exception_fp_ieee_inexact 0
		.amdhsa_exception_int_div_zero 0
	.end_amdhsa_kernel

; #define LAS __attribute__((address_space(3)))
; __global__ void __launch_bounds__(512, 2) mega_fwd(Args a) {
;     extern __shared__ __attribute__((aligned(16))) unsigned char lds_raw[];
;     LAS unsigned char* lds = (LAS unsigned char*)lds_raw;
;     cg::grid_group grid = cg::this_grid();
;     const int tid = threadIdx.x, lane = tid & 63, wave = __builtin_amdgcn_readfirstlane(tid >> 6);
amdhsa.kernels:
  - .agpr_count:     0
    .args:
      - .offset:         0
        .size:           216
        .value_kind:     by_value
      - .offset:         216
        .size:           4
        .value_kind:     hidden_block_count_x
      - .offset:         220
        .size:           4
        .value_kind:     hidden_block_count_y
      - .offset:         224
        .size:           4
        .value_kind:     hidden_block_count_z
      - .offset:         228
        .size:           2
        .value_kind:     hidden_group_size_x
      - .offset:         230
        .size:           2
        .value_kind:     hidden_group_size_y
      - .offset:         232
        .size:           2
        .value_kind:     hidden_group_size_z
      - .offset:         234
        .size:           2
        .value_kind:     hidden_remainder_x
      - .offset:         236
        .size:           2
        .value_kind:     hidden_remainder_y
      - .offset:         238
        .size:           2
        .value_kind:     hidden_remainder_z
      - .offset:         256
        .size:           8
        .value_kind:     hidden_global_offset_x
      - .offset:         264
        .size:           8
        .value_kind:     hidden_global_offset_y
      - .offset:         272
        .size:           8
        .value_kind:     hidden_global_offset_z
      - .offset:         280
        .size:           2
        .value_kind:     hidden_grid_dims
      - .offset:         304
        .size:           8
        .value_kind:     hidden_multigrid_sync_arg
      - .offset:         336
        .size:           4
        .value_kind:     hidden_dynamic_lds_size
    .group_segment_fixed_size: 0
    .kernarg_segment_align: 8
    .kernarg_segment_size: 472
    .language:       OpenCL C
    .language_version:
      - 2
      - 0
    .max_flat_workgroup_size: 512
    .name:           _Z8mega_fwd4Args
    .private_segment_fixed_size: 0
    .sgpr_count:     108
    .sgpr_spill_count: 48
    .symbol:         _Z8mega_fwd4Args.kd
    .uniform_work_group_size: 1
    .uses_dynamic_stack: false
    .vgpr_count:     255
    .vgpr_spill_count: 0
    .wavefront_size: 64
